# cross-attention: X2/X3 units follow X1 tile order so the q-proj->scores->PV chain stays in one workgroup (no grid barrier after X1, X2); filter_gen W3 via ds_read_b128
# baseline (speedup 1.0000x reference)
; DI void filter_gen(const Inputs& in, int l, unsigned char* ws, LAS unsigned char* lds, int vcu, int G, int wave, int tid) {
;     ...
;     for (int it = wgi * 8 + wave; it < 4096 + 2048; it += nwg * 8) {
;         const int g = it >= 4096, t = g ? it - 4096 : it, L = g ? 2048 : 4096, FRS = g ? FRS1 : FRS0;
;         bf16_t* FR = (bf16_t*)(ws + (g ? WS_FR1 : WS_FR0)); bf16_t* FRO = (bf16_t*)(ws + (g ? WS_FRO1 : WS_FRO0));
;         const float tl = (float)t / (float)(L - 1);
;         const float w = 6.2831853071795864769f * (float)t / (float)L;
;         float z;
;         { const int k = lane; const int fi = (k >= 17) ? k - 17 : k - 1; const float f = 1e-4f + (float)fi * ((15.0f - 1e-4f) / 15.0f);
;           z = (k == 0) ? tl : (k <= 16 ? __cosf(f * w) : -__sinf(f * w)); if (k > 32) z = 0.f; }
;         float a = Bs[lane];
; #pragma unroll 11
;         for (int k = 0; k < 33; ++k) a += __shfl(z, k) * W1s[k * 64 + lane];
;         const float h1 = __sinf(a);
;         a = Bs[64 + lane];
; #pragma unroll 16
;         for (int k = 0; k < 64; ++k) a += __shfl(h1, k) * W2s[k * 64 + lane];
;         const float h2 = __sinf(a);
;         float o[4] = {0.f, 0.f, 0.f, 0.f};
; #pragma unroll 16
;         for (int k = 0; k < 64; ++k) { const float hk = __shfl(h2, k);
; #pragma unroll
;             for (int q = 0; q < 4; ++q) o[q] += hk * W3s[k * 256 + lane + 64 * q]; }
; #pragma unroll
;         for (int q = 0; q < 4; ++q) {
;             const int cidx = 256 * chunk + lane + 64 * q, dir = cidx >> 9, c = cidx & 511;
;             const float delta = fabsf(-3.0701134573253942f + (float)c * ((-15.350567286626972f + 3.0701134573253942f) / 511.0f));
;             const float val = o[q] * __expf(-tl * delta);
;             bf16_t* row = FR + (size_t)c * FRS; bf16_t* rowo = FRO + (size_t)c * FRS;
.LBB0_51:
	s_or_b64 exec, exec, s[0:1]
	s_lshl_b32 s0, s76, 1
	s_and_b32 s0, s0, -8
	s_add_i32 s30, s0, s43
	s_cmpk_gt_i32 s30, 0x17ff
	s_waitcnt lgkmcnt(0)
	s_barrier
	s_cbranch_scc1 .LBB0_90
	v_not_b32_e32 v2, 16
	v_cmp_lt_u32_e64 s[2:3], 16, v60
	s_lshl_b32 s0, s8, 8
	s_and_b32 s0, s0, 0x100
	v_cndmask_b32_e64 v2, -1, v2, s[2:3]
	v_add_u32_e32 v2, v2, v60
	v_cvt_f32_i32_e32 v2, v2
	v_lshl_or_b32 v16, v60, 2, s0
	v_mov_b32_e32 v14, 0x38d1b717
	v_lshl_add_u32 v15, v60, 2, 0
	v_cvt_f32_u32_e32 v4, v16
	v_fmac_f32_e32 v14, 0x3f7fff90, v2
	v_add_u32_e32 v2, 0x16100, v15
	v_or_b32_e32 v18, 1, v16
	v_or_b32_e32 v19, 2, v16
	v_or_b32_e32 v20, 3, v16
	s_sub_i32 s1, s42, s8
	ds_read2st64_b32 v[2:3], v2 offset1:1
	v_cvt_f32_u32_e32 v5, v18
	v_cvt_f32_u32_e32 v6, v19
	v_cvt_f32_u32_e32 v7, v20
	s_lshl_b32 s1, s1, 1
	v_mov_b32_e32 v17, 0xc0447cbd
	s_cmp_gt_u32 s8, 1
	v_fmamk_f32 v21, v4, 0xbcc4df2d, v17
	v_lshlrev_b32_e32 v4, 2, v249
	s_cselect_b64 s[18:19], -1, 0
	s_add_i32 s1, s1, 6
	v_and_b32_e32 v24, 0x100, v4
	s_mov_b32 s17, 0
	v_cmp_ne_u32_e64 s[4:5], 0, v60
	v_cmp_lt_u32_e64 s[6:7], 32, v60
	s_and_b32 s31, s1, -8
	v_fmamk_f32 v22, v5, 0xbcc4df2d, v17
	v_fmamk_f32 v23, v6, 0xbcc4df2d, v17
	v_fmac_f32_e32 v17, 0xbcc4df2d, v7
	v_or_b32_e32 v25, 40, v24
	v_add_u32_e32 v26, 0x12100, v15
	s_movk_i32 s41, 0x800
	s_mov_b32 s43, 0xc10000
	s_mov_b32 s44, 0x1e510000
	s_movk_i32 s45, 0x1040
	v_mov_b32_e32 v5, 0
	v_readlane_b32 s16, v255, 3
	s_lshr_b32 s0, s8, 1
	s_sub_i32 s1, 7, s16
	s_cmp_eq_u32 s0, 0
	s_cselect_b32 s1, s1, s16
	s_lshl_b32 s1, s1, 1
	s_add_i32 s1, s1, 0x18000
	s_and_b32 s10, s16, 3
	s_lshl_b32 s11, s10, 6
	s_lshl_b32 s10, s10, 10
	s_add_i32 s10, s10, 0x18000
	s_and_b32 s0, s8, 1
	s_lshl_b32 s0, s0, 8
	s_add_i32 s0, s0, s11
	v_lshl_add_u32 v40, v249, 6, s1
	v_lshl_add_u32 v41, v249, 4, s10
	v_add_u32_e32 v42, s0, v249
	v_lshlrev_b32_e32 v43, 4, v249
	s_branch .LBB0_54

; DI void filter_gen(const Inputs& in, int l, unsigned char* ws, LAS unsigned char* lds, int vcu, int G, int wave, int tid) {
;     ...
;         float a = Bs[lane];
; #pragma unroll 11
;         for (int k = 0; k < 33; ++k) a += __shfl(z, k) * W1s[k * 64 + lane];
;         const float h1 = __sinf(a);
;         a = Bs[64 + lane];
; #pragma unroll 16
;         for (int k = 0; k < 64; ++k) a += __shfl(h1, k) * W2s[k * 64 + lane];
;         const float h2 = __sinf(a);
.LBB0_60:
	s_or_b64 exec, exec, s[0:1]
	v_cndmask_b32_e64 v4, v4, 0, s[6:7]
	s_waitcnt lgkmcnt(0)
	v_add_u32_e32 v6, 0x10000, v15
	ds_read2st64_b32 v[62:63], v6 offset0:0 offset1:1
	ds_read2st64_b32 v[64:65], v6 offset0:2 offset1:3
	ds_read2st64_b32 v[66:67], v6 offset0:4 offset1:5
	ds_read2st64_b32 v[68:69], v6 offset0:6 offset1:7
	ds_read2st64_b32 v[70:71], v6 offset0:8 offset1:9
	ds_read2st64_b32 v[72:73], v6 offset0:10 offset1:11
	ds_read2st64_b32 v[74:75], v6 offset0:12 offset1:13
	ds_read2st64_b32 v[76:77], v6 offset0:14 offset1:15
	ds_read2st64_b32 v[78:79], v6 offset0:16 offset1:17
	ds_read2st64_b32 v[80:81], v6 offset0:18 offset1:19
	ds_read2st64_b32 v[82:83], v6 offset0:20 offset1:21
	ds_read2st64_b32 v[84:85], v6 offset0:22 offset1:23
	ds_read2st64_b32 v[86:87], v6 offset0:24 offset1:25
	ds_read2st64_b32 v[88:89], v6 offset0:26 offset1:27
	ds_read2st64_b32 v[90:91], v6 offset0:28 offset1:29
	ds_read2st64_b32 v[92:93], v6 offset0:30 offset1:31
	ds_read_b32 v28, v6 offset:8192
	v_mov_b32_e32 v7, v2
	s_waitcnt lgkmcnt(8)
	v_readlane_b32 s0, v4, 0
	v_readlane_b32 s10, v4, 1
	v_readlane_b32 s20, v4, 2
	v_readlane_b32 s28, v4, 3
	v_fmac_f32_e32 v7, s0, v62
	v_fmac_f32_e32 v7, s10, v63
	v_fmac_f32_e32 v7, s20, v64
	v_fmac_f32_e32 v7, s28, v65
	v_readlane_b32 s0, v4, 4
	v_readlane_b32 s10, v4, 5
	v_readlane_b32 s20, v4, 6
	v_readlane_b32 s28, v4, 7
	v_fmac_f32_e32 v7, s0, v66
	v_fmac_f32_e32 v7, s10, v67
	v_fmac_f32_e32 v7, s20, v68
	v_fmac_f32_e32 v7, s28, v69
	v_readlane_b32 s0, v4, 8
	v_readlane_b32 s10, v4, 9
	v_readlane_b32 s20, v4, 10
	v_readlane_b32 s28, v4, 11
	v_fmac_f32_e32 v7, s0, v70
	v_fmac_f32_e32 v7, s10, v71
	v_fmac_f32_e32 v7, s20, v72
	v_fmac_f32_e32 v7, s28, v73
	v_readlane_b32 s0, v4, 12
	v_readlane_b32 s10, v4, 13
	v_readlane_b32 s20, v4, 14
	v_readlane_b32 s28, v4, 15
	v_fmac_f32_e32 v7, s0, v74
	v_fmac_f32_e32 v7, s10, v75
	v_fmac_f32_e32 v7, s20, v76
	v_fmac_f32_e32 v7, s28, v77
	s_waitcnt lgkmcnt(0)
	v_readlane_b32 s0, v4, 16
	v_readlane_b32 s10, v4, 17
	v_readlane_b32 s20, v4, 18
	v_readlane_b32 s28, v4, 19
	v_fmac_f32_e32 v7, s0, v78
	v_fmac_f32_e32 v7, s10, v79
	v_fmac_f32_e32 v7, s20, v80
	v_fmac_f32_e32 v7, s28, v81
	v_readlane_b32 s0, v4, 20
	v_readlane_b32 s10, v4, 21
	v_readlane_b32 s20, v4, 22
	v_readlane_b32 s28, v4, 23
	v_fmac_f32_e32 v7, s0, v82
	v_fmac_f32_e32 v7, s10, v83
	v_fmac_f32_e32 v7, s20, v84
	v_fmac_f32_e32 v7, s28, v85
	v_readlane_b32 s0, v4, 24
	v_readlane_b32 s10, v4, 25
	v_readlane_b32 s20, v4, 26
	v_readlane_b32 s28, v4, 27
	v_fmac_f32_e32 v7, s0, v86
	v_fmac_f32_e32 v7, s10, v87
	v_fmac_f32_e32 v7, s20, v88
	v_fmac_f32_e32 v7, s28, v89
	v_readlane_b32 s0, v4, 28
	v_readlane_b32 s10, v4, 29
	v_readlane_b32 s20, v4, 30
	v_readlane_b32 s28, v4, 31
	v_fmac_f32_e32 v7, s0, v90
	v_fmac_f32_e32 v7, s10, v91
	v_fmac_f32_e32 v7, s20, v92
	v_fmac_f32_e32 v7, s28, v93
	v_readlane_b32 s0, v4, 32
	s_nop 1
	v_fmac_f32_e32 v7, s0, v28
	v_mul_f32_e32 v4, 0.15915494, v7
	v_sin_f32_e32 v4, v4
	ds_read2st64_b32 v[62:63], v26 offset0:0 offset1:1
	ds_read2st64_b32 v[64:65], v26 offset0:2 offset1:3
	ds_read2st64_b32 v[66:67], v26 offset0:4 offset1:5
	ds_read2st64_b32 v[68:69], v26 offset0:6 offset1:7
	ds_read2st64_b32 v[70:71], v26 offset0:8 offset1:9
	ds_read2st64_b32 v[72:73], v26 offset0:10 offset1:11
	ds_read2st64_b32 v[74:75], v26 offset0:12 offset1:13
	ds_read2st64_b32 v[76:77], v26 offset0:14 offset1:15
	ds_read2st64_b32 v[78:79], v26 offset0:16 offset1:17
	ds_read2st64_b32 v[80:81], v26 offset0:18 offset1:19
	ds_read2st64_b32 v[82:83], v26 offset0:20 offset1:21
	ds_read2st64_b32 v[84:85], v26 offset0:22 offset1:23
	ds_read2st64_b32 v[86:87], v26 offset0:24 offset1:25
	ds_read2st64_b32 v[88:89], v26 offset0:26 offset1:27
	ds_read2st64_b32 v[90:91], v26 offset0:28 offset1:29
	ds_read2st64_b32 v[92:93], v26 offset0:30 offset1:31
	ds_read2st64_b32 v[94:95], v26 offset0:32 offset1:33
	ds_read2st64_b32 v[96:97], v26 offset0:34 offset1:35
	ds_read2st64_b32 v[98:99], v26 offset0:36 offset1:37
	ds_read2st64_b32 v[100:101], v26 offset0:38 offset1:39
	ds_read2st64_b32 v[102:103], v26 offset0:40 offset1:41
	ds_read2st64_b32 v[104:105], v26 offset0:42 offset1:43
	ds_read2st64_b32 v[106:107], v26 offset0:44 offset1:45
	ds_read2st64_b32 v[108:109], v26 offset0:46 offset1:47
	ds_read2st64_b32 v[110:111], v26 offset0:48 offset1:49
	ds_read2st64_b32 v[112:113], v26 offset0:50 offset1:51
	ds_read2st64_b32 v[114:115], v26 offset0:52 offset1:53
	ds_read2st64_b32 v[116:117], v26 offset0:54 offset1:55
	ds_read2st64_b32 v[118:119], v26 offset0:56 offset1:57
	ds_read2st64_b32 v[120:121], v26 offset0:58 offset1:59
	ds_read2st64_b32 v[122:123], v26 offset0:60 offset1:61
	ds_read2st64_b32 v[124:125], v26 offset0:62 offset1:63
	v_mov_b32_e32 v7, v3
	s_waitcnt lgkmcnt(15)
; DI void filter_gen(const Inputs& in, int l, unsigned char* ws, LAS unsigned char* lds, int vcu, int G, int wave, int tid) {
;     ...
;         a = Bs[64 + lane];
; #pragma unroll 16
;         for (int k = 0; k < 64; ++k) a += __shfl(h1, k) * W2s[k * 64 + lane];
;         const float h2 = __sinf(a);
;         float o[4] = {0.f, 0.f, 0.f, 0.f};
; #pragma unroll 16
;         for (int k = 0; k < 64; ++k) { const float hk = __shfl(h2, k);
; #pragma unroll
;             for (int q = 0; q < 4; ++q) o[q] += hk * W3s[k * 256 + lane + 64 * q]; }
	v_readlane_b32 s0, v4, 0
	v_readlane_b32 s10, v4, 1
	v_readlane_b32 s20, v4, 2
	v_readlane_b32 s28, v4, 3
	v_fmac_f32_e32 v7, s0, v62
	v_fmac_f32_e32 v7, s10, v63
	v_fmac_f32_e32 v7, s20, v64
	v_fmac_f32_e32 v7, s28, v65
	v_readlane_b32 s0, v4, 4
	v_readlane_b32 s10, v4, 5
	v_readlane_b32 s20, v4, 6
	v_readlane_b32 s28, v4, 7
	v_fmac_f32_e32 v7, s0, v66
	v_fmac_f32_e32 v7, s10, v67
	v_fmac_f32_e32 v7, s20, v68
	v_fmac_f32_e32 v7, s28, v69
	v_readlane_b32 s0, v4, 8
	v_readlane_b32 s10, v4, 9
	v_readlane_b32 s20, v4, 10
	v_readlane_b32 s28, v4, 11
	v_fmac_f32_e32 v7, s0, v70
	v_fmac_f32_e32 v7, s10, v71
	v_fmac_f32_e32 v7, s20, v72
	v_fmac_f32_e32 v7, s28, v73
	v_readlane_b32 s0, v4, 12
	v_readlane_b32 s10, v4, 13
	v_readlane_b32 s20, v4, 14
	v_readlane_b32 s28, v4, 15
	v_fmac_f32_e32 v7, s0, v74
	v_fmac_f32_e32 v7, s10, v75
	v_fmac_f32_e32 v7, s20, v76
	v_fmac_f32_e32 v7, s28, v77
	v_readlane_b32 s0, v4, 16
	v_readlane_b32 s10, v4, 17
	v_readlane_b32 s20, v4, 18
	v_readlane_b32 s28, v4, 19
	v_fmac_f32_e32 v7, s0, v78
	v_fmac_f32_e32 v7, s10, v79
	v_fmac_f32_e32 v7, s20, v80
	v_fmac_f32_e32 v7, s28, v81
	v_readlane_b32 s0, v4, 20
	v_readlane_b32 s10, v4, 21
	v_readlane_b32 s20, v4, 22
	v_readlane_b32 s28, v4, 23
	v_fmac_f32_e32 v7, s0, v82
	v_fmac_f32_e32 v7, s10, v83
	v_fmac_f32_e32 v7, s20, v84
	v_fmac_f32_e32 v7, s28, v85
	v_readlane_b32 s0, v4, 24
	v_readlane_b32 s10, v4, 25
	v_readlane_b32 s20, v4, 26
	v_readlane_b32 s28, v4, 27
	v_fmac_f32_e32 v7, s0, v86
	v_fmac_f32_e32 v7, s10, v87
	v_fmac_f32_e32 v7, s20, v88
	v_fmac_f32_e32 v7, s28, v89
	v_readlane_b32 s0, v4, 28
	v_readlane_b32 s10, v4, 29
	v_readlane_b32 s20, v4, 30
	v_readlane_b32 s28, v4, 31
	v_fmac_f32_e32 v7, s0, v90
	v_fmac_f32_e32 v7, s10, v91
	v_fmac_f32_e32 v7, s20, v92
	v_fmac_f32_e32 v7, s28, v93
	s_waitcnt lgkmcnt(0)
	v_readlane_b32 s0, v4, 32
	v_readlane_b32 s10, v4, 33
	v_readlane_b32 s20, v4, 34
	v_readlane_b32 s28, v4, 35
	v_fmac_f32_e32 v7, s0, v94
	v_fmac_f32_e32 v7, s10, v95
	v_fmac_f32_e32 v7, s20, v96
	v_fmac_f32_e32 v7, s28, v97
	v_readlane_b32 s0, v4, 36
	v_readlane_b32 s10, v4, 37
	v_readlane_b32 s20, v4, 38
	v_readlane_b32 s28, v4, 39
	v_fmac_f32_e32 v7, s0, v98
	v_fmac_f32_e32 v7, s10, v99
	v_fmac_f32_e32 v7, s20, v100
	v_fmac_f32_e32 v7, s28, v101
	v_readlane_b32 s0, v4, 40
	v_readlane_b32 s10, v4, 41
	v_readlane_b32 s20, v4, 42
	v_readlane_b32 s28, v4, 43
	v_fmac_f32_e32 v7, s0, v102
	v_fmac_f32_e32 v7, s10, v103
	v_fmac_f32_e32 v7, s20, v104
	v_fmac_f32_e32 v7, s28, v105
	v_readlane_b32 s0, v4, 44
	v_readlane_b32 s10, v4, 45
	v_readlane_b32 s20, v4, 46
	v_readlane_b32 s28, v4, 47
	v_fmac_f32_e32 v7, s0, v106
	v_fmac_f32_e32 v7, s10, v107
	v_fmac_f32_e32 v7, s20, v108
	v_fmac_f32_e32 v7, s28, v109
	v_readlane_b32 s0, v4, 48
	v_readlane_b32 s10, v4, 49
	v_readlane_b32 s20, v4, 50
	v_readlane_b32 s28, v4, 51
	v_fmac_f32_e32 v7, s0, v110
	v_fmac_f32_e32 v7, s10, v111
	v_fmac_f32_e32 v7, s20, v112
	v_fmac_f32_e32 v7, s28, v113
	v_readlane_b32 s0, v4, 52
	v_readlane_b32 s10, v4, 53
	v_readlane_b32 s20, v4, 54
	v_readlane_b32 s28, v4, 55
	v_fmac_f32_e32 v7, s0, v114
	v_fmac_f32_e32 v7, s10, v115
	v_fmac_f32_e32 v7, s20, v116
	v_fmac_f32_e32 v7, s28, v117
	v_readlane_b32 s0, v4, 56
	v_readlane_b32 s10, v4, 57
	v_readlane_b32 s20, v4, 58
	v_readlane_b32 s28, v4, 59
	v_fmac_f32_e32 v7, s0, v118
	v_fmac_f32_e32 v7, s10, v119
	v_fmac_f32_e32 v7, s20, v120
	v_fmac_f32_e32 v7, s28, v121
	v_readlane_b32 s0, v4, 60
	v_readlane_b32 s10, v4, 61
	v_readlane_b32 s20, v4, 62
	v_readlane_b32 s28, v4, 63
	v_fmac_f32_e32 v7, s0, v122
	v_fmac_f32_e32 v7, s10, v123
	v_fmac_f32_e32 v7, s20, v124
	v_fmac_f32_e32 v7, s28, v125
	v_mul_f32_e32 v4, 0.15915494, v7
	v_sin_f32_e32 v4, v4
	ds_read_b128 v[62:65], v43
	ds_read_b128 v[66:69], v43 offset:1024
	ds_read_b128 v[70:73], v43 offset:2048
	ds_read_b128 v[74:77], v43 offset:3072
	ds_read_b128 v[78:81], v43 offset:4096
	ds_read_b128 v[82:85], v43 offset:5120
	ds_read_b128 v[86:89], v43 offset:6144
	ds_read_b128 v[90:93], v43 offset:7168
	ds_read_b128 v[94:97], v43 offset:8192
	ds_read_b128 v[98:101], v43 offset:9216
	ds_read_b128 v[102:105], v43 offset:10240
	ds_read_b128 v[106:109], v43 offset:11264
	ds_read_b128 v[110:113], v43 offset:12288
	ds_read_b128 v[114:117], v43 offset:13312
	ds_read_b128 v[118:121], v43 offset:14336
	ds_read_b128 v[122:125], v43 offset:15360
	v_mov_b32_e32 v8, 0
	v_mov_b32_e32 v9, 0
	v_mov_b32_e32 v6, 0
	v_mov_b32_e32 v7, 0
	s_waitcnt lgkmcnt(8)
	v_readlane_b32 s0, v4, 0
	v_readlane_b32 s10, v4, 1
	v_readlane_b32 s20, v4, 2
	v_readlane_b32 s28, v4, 3
	v_pk_fma_f32 v[8:9], v[62:63], s[0:1], v[8:9] op_sel_hi:[1,0,1]
	v_pk_fma_f32 v[6:7], v[64:65], s[0:1], v[6:7] op_sel_hi:[1,0,1]
	v_pk_fma_f32 v[8:9], v[66:67], s[10:11], v[8:9] op_sel_hi:[1,0,1]
	v_pk_fma_f32 v[6:7], v[68:69], s[10:11], v[6:7] op_sel_hi:[1,0,1]
	v_pk_fma_f32 v[8:9], v[70:71], s[20:21], v[8:9] op_sel_hi:[1,0,1]
	v_pk_fma_f32 v[6:7], v[72:73], s[20:21], v[6:7] op_sel_hi:[1,0,1]
	v_pk_fma_f32 v[8:9], v[74:75], s[28:29], v[8:9] op_sel_hi:[1,0,1]
	v_pk_fma_f32 v[6:7], v[76:77], s[28:29], v[6:7] op_sel_hi:[1,0,1]
	v_readlane_b32 s0, v4, 4
	v_readlane_b32 s10, v4, 5
	v_readlane_b32 s20, v4, 6
	v_readlane_b32 s28, v4, 7
	v_pk_fma_f32 v[8:9], v[78:79], s[0:1], v[8:9] op_sel_hi:[1,0,1]
	v_pk_fma_f32 v[6:7], v[80:81], s[0:1], v[6:7] op_sel_hi:[1,0,1]
	v_pk_fma_f32 v[8:9], v[82:83], s[10:11], v[8:9] op_sel_hi:[1,0,1]
	v_pk_fma_f32 v[6:7], v[84:85], s[10:11], v[6:7] op_sel_hi:[1,0,1]
	v_pk_fma_f32 v[8:9], v[86:87], s[20:21], v[8:9] op_sel_hi:[1,0,1]
	v_pk_fma_f32 v[6:7], v[88:89], s[20:21], v[6:7] op_sel_hi:[1,0,1]
	v_pk_fma_f32 v[8:9], v[90:91], s[28:29], v[8:9] op_sel_hi:[1,0,1]
	v_pk_fma_f32 v[6:7], v[92:93], s[28:29], v[6:7] op_sel_hi:[1,0,1]
	ds_read_b128 v[62:65], v43 offset:16384
	ds_read_b128 v[66:69], v43 offset:17408
	ds_read_b128 v[70:73], v43 offset:18432
	ds_read_b128 v[74:77], v43 offset:19456
	ds_read_b128 v[78:81], v43 offset:20480
	ds_read_b128 v[82:85], v43 offset:21504
	ds_read_b128 v[86:89], v43 offset:22528
	ds_read_b128 v[90:93], v43 offset:23552
	s_waitcnt lgkmcnt(8)
; DI void filter_gen(const Inputs& in, int l, unsigned char* ws, LAS unsigned char* lds, int vcu, int G, int wave, int tid) {
;     ...
;         float o[4] = {0.f, 0.f, 0.f, 0.f};
; #pragma unroll 16
;         for (int k = 0; k < 64; ++k) { const float hk = __shfl(h2, k);
; #pragma unroll
;             for (int q = 0; q < 4; ++q) o[q] += hk * W3s[k * 256 + lane + 64 * q]; }
	v_readlane_b32 s0, v4, 8
	v_readlane_b32 s10, v4, 9
	v_readlane_b32 s20, v4, 10
	v_readlane_b32 s28, v4, 11
	v_pk_fma_f32 v[8:9], v[94:95], s[0:1], v[8:9] op_sel_hi:[1,0,1]
	v_pk_fma_f32 v[6:7], v[96:97], s[0:1], v[6:7] op_sel_hi:[1,0,1]
	v_pk_fma_f32 v[8:9], v[98:99], s[10:11], v[8:9] op_sel_hi:[1,0,1]
	v_pk_fma_f32 v[6:7], v[100:101], s[10:11], v[6:7] op_sel_hi:[1,0,1]
	v_pk_fma_f32 v[8:9], v[102:103], s[20:21], v[8:9] op_sel_hi:[1,0,1]
	v_pk_fma_f32 v[6:7], v[104:105], s[20:21], v[6:7] op_sel_hi:[1,0,1]
	v_pk_fma_f32 v[8:9], v[106:107], s[28:29], v[8:9] op_sel_hi:[1,0,1]
	v_pk_fma_f32 v[6:7], v[108:109], s[28:29], v[6:7] op_sel_hi:[1,0,1]
	v_readlane_b32 s0, v4, 12
	v_readlane_b32 s10, v4, 13
	v_readlane_b32 s20, v4, 14
	v_readlane_b32 s28, v4, 15
	v_pk_fma_f32 v[8:9], v[110:111], s[0:1], v[8:9] op_sel_hi:[1,0,1]
	v_pk_fma_f32 v[6:7], v[112:113], s[0:1], v[6:7] op_sel_hi:[1,0,1]
	v_pk_fma_f32 v[8:9], v[114:115], s[10:11], v[8:9] op_sel_hi:[1,0,1]
	v_pk_fma_f32 v[6:7], v[116:117], s[10:11], v[6:7] op_sel_hi:[1,0,1]
	v_pk_fma_f32 v[8:9], v[118:119], s[20:21], v[8:9] op_sel_hi:[1,0,1]
	v_pk_fma_f32 v[6:7], v[120:121], s[20:21], v[6:7] op_sel_hi:[1,0,1]
	v_pk_fma_f32 v[8:9], v[122:123], s[28:29], v[8:9] op_sel_hi:[1,0,1]
	v_pk_fma_f32 v[6:7], v[124:125], s[28:29], v[6:7] op_sel_hi:[1,0,1]
	ds_read_b128 v[94:97], v43 offset:24576
	ds_read_b128 v[98:101], v43 offset:25600
	ds_read_b128 v[102:105], v43 offset:26624
	ds_read_b128 v[106:109], v43 offset:27648
	ds_read_b128 v[110:113], v43 offset:28672
	ds_read_b128 v[114:117], v43 offset:29696
	ds_read_b128 v[118:121], v43 offset:30720
	ds_read_b128 v[122:125], v43 offset:31744
	s_waitcnt lgkmcnt(8)
	v_readlane_b32 s0, v4, 16
	v_readlane_b32 s10, v4, 17
	v_readlane_b32 s20, v4, 18
	v_readlane_b32 s28, v4, 19
	v_pk_fma_f32 v[8:9], v[62:63], s[0:1], v[8:9] op_sel_hi:[1,0,1]
	v_pk_fma_f32 v[6:7], v[64:65], s[0:1], v[6:7] op_sel_hi:[1,0,1]
	v_pk_fma_f32 v[8:9], v[66:67], s[10:11], v[8:9] op_sel_hi:[1,0,1]
	v_pk_fma_f32 v[6:7], v[68:69], s[10:11], v[6:7] op_sel_hi:[1,0,1]
	v_pk_fma_f32 v[8:9], v[70:71], s[20:21], v[8:9] op_sel_hi:[1,0,1]
	v_pk_fma_f32 v[6:7], v[72:73], s[20:21], v[6:7] op_sel_hi:[1,0,1]
	v_pk_fma_f32 v[8:9], v[74:75], s[28:29], v[8:9] op_sel_hi:[1,0,1]
	v_pk_fma_f32 v[6:7], v[76:77], s[28:29], v[6:7] op_sel_hi:[1,0,1]
	v_readlane_b32 s0, v4, 20
	v_readlane_b32 s10, v4, 21
	v_readlane_b32 s20, v4, 22
	v_readlane_b32 s28, v4, 23
	v_pk_fma_f32 v[8:9], v[78:79], s[0:1], v[8:9] op_sel_hi:[1,0,1]
	v_pk_fma_f32 v[6:7], v[80:81], s[0:1], v[6:7] op_sel_hi:[1,0,1]
	v_pk_fma_f32 v[8:9], v[82:83], s[10:11], v[8:9] op_sel_hi:[1,0,1]
	v_pk_fma_f32 v[6:7], v[84:85], s[10:11], v[6:7] op_sel_hi:[1,0,1]
	v_pk_fma_f32 v[8:9], v[86:87], s[20:21], v[8:9] op_sel_hi:[1,0,1]
	v_pk_fma_f32 v[6:7], v[88:89], s[20:21], v[6:7] op_sel_hi:[1,0,1]
	v_pk_fma_f32 v[8:9], v[90:91], s[28:29], v[8:9] op_sel_hi:[1,0,1]
	v_pk_fma_f32 v[6:7], v[92:93], s[28:29], v[6:7] op_sel_hi:[1,0,1]
	ds_read_b128 v[62:65], v43 offset:32768
	ds_read_b128 v[66:69], v43 offset:33792
	ds_read_b128 v[70:73], v43 offset:34816
	ds_read_b128 v[74:77], v43 offset:35840
	ds_read_b128 v[78:81], v43 offset:36864
	ds_read_b128 v[82:85], v43 offset:37888
	ds_read_b128 v[86:89], v43 offset:38912
	ds_read_b128 v[90:93], v43 offset:39936
	s_waitcnt lgkmcnt(8)
	v_readlane_b32 s0, v4, 24
	v_readlane_b32 s10, v4, 25
	v_readlane_b32 s20, v4, 26
	v_readlane_b32 s28, v4, 27
	v_pk_fma_f32 v[8:9], v[94:95], s[0:1], v[8:9] op_sel_hi:[1,0,1]
	v_pk_fma_f32 v[6:7], v[96:97], s[0:1], v[6:7] op_sel_hi:[1,0,1]
	v_pk_fma_f32 v[8:9], v[98:99], s[10:11], v[8:9] op_sel_hi:[1,0,1]
	v_pk_fma_f32 v[6:7], v[100:101], s[10:11], v[6:7] op_sel_hi:[1,0,1]
	v_pk_fma_f32 v[8:9], v[102:103], s[20:21], v[8:9] op_sel_hi:[1,0,1]
	v_pk_fma_f32 v[6:7], v[104:105], s[20:21], v[6:7] op_sel_hi:[1,0,1]
	v_pk_fma_f32 v[8:9], v[106:107], s[28:29], v[8:9] op_sel_hi:[1,0,1]
	v_pk_fma_f32 v[6:7], v[108:109], s[28:29], v[6:7] op_sel_hi:[1,0,1]
	v_readlane_b32 s0, v4, 28
	v_readlane_b32 s10, v4, 29
	v_readlane_b32 s20, v4, 30
	v_readlane_b32 s28, v4, 31
	v_pk_fma_f32 v[8:9], v[110:111], s[0:1], v[8:9] op_sel_hi:[1,0,1]
	v_pk_fma_f32 v[6:7], v[112:113], s[0:1], v[6:7] op_sel_hi:[1,0,1]
	v_pk_fma_f32 v[8:9], v[114:115], s[10:11], v[8:9] op_sel_hi:[1,0,1]
	v_pk_fma_f32 v[6:7], v[116:117], s[10:11], v[6:7] op_sel_hi:[1,0,1]
	v_pk_fma_f32 v[8:9], v[118:119], s[20:21], v[8:9] op_sel_hi:[1,0,1]
	v_pk_fma_f32 v[6:7], v[120:121], s[20:21], v[6:7] op_sel_hi:[1,0,1]
	v_pk_fma_f32 v[8:9], v[122:123], s[28:29], v[8:9] op_sel_hi:[1,0,1]
	v_pk_fma_f32 v[6:7], v[124:125], s[28:29], v[6:7] op_sel_hi:[1,0,1]
	ds_read_b128 v[94:97], v43 offset:40960
	ds_read_b128 v[98:101], v43 offset:41984
	ds_read_b128 v[102:105], v43 offset:43008
	ds_read_b128 v[106:109], v43 offset:44032
	ds_read_b128 v[110:113], v43 offset:45056
	ds_read_b128 v[114:117], v43 offset:46080
	ds_read_b128 v[118:121], v43 offset:47104
	ds_read_b128 v[122:125], v43 offset:48128
	s_waitcnt lgkmcnt(8)
; DI void filter_gen(const Inputs& in, int l, unsigned char* ws, LAS unsigned char* lds, int vcu, int G, int wave, int tid) {
;     ...
;         float o[4] = {0.f, 0.f, 0.f, 0.f};
; #pragma unroll 16
;         for (int k = 0; k < 64; ++k) { const float hk = __shfl(h2, k);
; #pragma unroll
;             for (int q = 0; q < 4; ++q) o[q] += hk * W3s[k * 256 + lane + 64 * q]; }
	v_readlane_b32 s0, v4, 32
	v_readlane_b32 s10, v4, 33
	v_readlane_b32 s20, v4, 34
	v_readlane_b32 s28, v4, 35
	v_pk_fma_f32 v[8:9], v[62:63], s[0:1], v[8:9] op_sel_hi:[1,0,1]
	v_pk_fma_f32 v[6:7], v[64:65], s[0:1], v[6:7] op_sel_hi:[1,0,1]
	v_pk_fma_f32 v[8:9], v[66:67], s[10:11], v[8:9] op_sel_hi:[1,0,1]
	v_pk_fma_f32 v[6:7], v[68:69], s[10:11], v[6:7] op_sel_hi:[1,0,1]
	v_pk_fma_f32 v[8:9], v[70:71], s[20:21], v[8:9] op_sel_hi:[1,0,1]
	v_pk_fma_f32 v[6:7], v[72:73], s[20:21], v[6:7] op_sel_hi:[1,0,1]
	v_pk_fma_f32 v[8:9], v[74:75], s[28:29], v[8:9] op_sel_hi:[1,0,1]
	v_pk_fma_f32 v[6:7], v[76:77], s[28:29], v[6:7] op_sel_hi:[1,0,1]
	v_readlane_b32 s0, v4, 36
	v_readlane_b32 s10, v4, 37
	v_readlane_b32 s20, v4, 38
	v_readlane_b32 s28, v4, 39
	v_pk_fma_f32 v[8:9], v[78:79], s[0:1], v[8:9] op_sel_hi:[1,0,1]
	v_pk_fma_f32 v[6:7], v[80:81], s[0:1], v[6:7] op_sel_hi:[1,0,1]
	v_pk_fma_f32 v[8:9], v[82:83], s[10:11], v[8:9] op_sel_hi:[1,0,1]
	v_pk_fma_f32 v[6:7], v[84:85], s[10:11], v[6:7] op_sel_hi:[1,0,1]
	v_pk_fma_f32 v[8:9], v[86:87], s[20:21], v[8:9] op_sel_hi:[1,0,1]
	v_pk_fma_f32 v[6:7], v[88:89], s[20:21], v[6:7] op_sel_hi:[1,0,1]
	v_pk_fma_f32 v[8:9], v[90:91], s[28:29], v[8:9] op_sel_hi:[1,0,1]
	v_pk_fma_f32 v[6:7], v[92:93], s[28:29], v[6:7] op_sel_hi:[1,0,1]
	ds_read_b128 v[62:65], v43 offset:49152
	ds_read_b128 v[66:69], v43 offset:50176
	ds_read_b128 v[70:73], v43 offset:51200
	ds_read_b128 v[74:77], v43 offset:52224
	ds_read_b128 v[78:81], v43 offset:53248
	ds_read_b128 v[82:85], v43 offset:54272
	ds_read_b128 v[86:89], v43 offset:55296
	ds_read_b128 v[90:93], v43 offset:56320
	s_waitcnt lgkmcnt(8)
	v_readlane_b32 s0, v4, 40
	v_readlane_b32 s10, v4, 41
	v_readlane_b32 s20, v4, 42
	v_readlane_b32 s28, v4, 43
	v_pk_fma_f32 v[8:9], v[94:95], s[0:1], v[8:9] op_sel_hi:[1,0,1]
	v_pk_fma_f32 v[6:7], v[96:97], s[0:1], v[6:7] op_sel_hi:[1,0,1]
	v_pk_fma_f32 v[8:9], v[98:99], s[10:11], v[8:9] op_sel_hi:[1,0,1]
	v_pk_fma_f32 v[6:7], v[100:101], s[10:11], v[6:7] op_sel_hi:[1,0,1]
	v_pk_fma_f32 v[8:9], v[102:103], s[20:21], v[8:9] op_sel_hi:[1,0,1]
	v_pk_fma_f32 v[6:7], v[104:105], s[20:21], v[6:7] op_sel_hi:[1,0,1]
	v_pk_fma_f32 v[8:9], v[106:107], s[28:29], v[8:9] op_sel_hi:[1,0,1]
	v_pk_fma_f32 v[6:7], v[108:109], s[28:29], v[6:7] op_sel_hi:[1,0,1]
	v_readlane_b32 s0, v4, 44
	v_readlane_b32 s10, v4, 45
	v_readlane_b32 s20, v4, 46
	v_readlane_b32 s28, v4, 47
	v_pk_fma_f32 v[8:9], v[110:111], s[0:1], v[8:9] op_sel_hi:[1,0,1]
	v_pk_fma_f32 v[6:7], v[112:113], s[0:1], v[6:7] op_sel_hi:[1,0,1]
	v_pk_fma_f32 v[8:9], v[114:115], s[10:11], v[8:9] op_sel_hi:[1,0,1]
	v_pk_fma_f32 v[6:7], v[116:117], s[10:11], v[6:7] op_sel_hi:[1,0,1]
	v_pk_fma_f32 v[8:9], v[118:119], s[20:21], v[8:9] op_sel_hi:[1,0,1]
	v_pk_fma_f32 v[6:7], v[120:121], s[20:21], v[6:7] op_sel_hi:[1,0,1]
	v_pk_fma_f32 v[8:9], v[122:123], s[28:29], v[8:9] op_sel_hi:[1,0,1]
	v_pk_fma_f32 v[6:7], v[124:125], s[28:29], v[6:7] op_sel_hi:[1,0,1]
	ds_read_b128 v[94:97], v43 offset:57344
	ds_read_b128 v[98:101], v43 offset:58368
	ds_read_b128 v[102:105], v43 offset:59392
	ds_read_b128 v[106:109], v43 offset:60416
	ds_read_b128 v[110:113], v43 offset:61440
	ds_read_b128 v[114:117], v43 offset:62464
	ds_read_b128 v[118:121], v43 offset:63488
	ds_read_b128 v[122:125], v43 offset:64512
	s_waitcnt lgkmcnt(8)
; DI void filter_gen(const Inputs& in, int l, unsigned char* ws, LAS unsigned char* lds, int vcu, int G, int wave, int tid) {
;     ...
;         float o[4] = {0.f, 0.f, 0.f, 0.f};
; #pragma unroll 16
;         for (int k = 0; k < 64; ++k) { const float hk = __shfl(h2, k);
; #pragma unroll
;             for (int q = 0; q < 4; ++q) o[q] += hk * W3s[k * 256 + lane + 64 * q]; }
; #pragma unroll
;         for (int q = 0; q < 4; ++q) {
;             const int cidx = 256 * chunk + lane + 64 * q, dir = cidx >> 9, c = cidx & 511;
;             const float delta = fabsf(-3.0701134573253942f + (float)c * ((-15.350567286626972f + 3.0701134573253942f) / 511.0f));
;             const float val = o[q] * __expf(-tl * delta);
;             bf16_t* row = FR + (size_t)c * FRS; bf16_t* rowo = FRO + (size_t)c * FRS;
;             if (dir == 0) { row[L - t] = f2bf(val); rowo[L - t - 1] = f2bf(val); }
;             else if (t >= 1) { row[L + t] = f2bf(val); rowo[L + t - 1] = f2bf(val); }
;         }
	v_readlane_b32 s0, v4, 48
	v_readlane_b32 s10, v4, 49
	v_readlane_b32 s20, v4, 50
	v_readlane_b32 s28, v4, 51
	v_pk_fma_f32 v[8:9], v[62:63], s[0:1], v[8:9] op_sel_hi:[1,0,1]
	v_pk_fma_f32 v[6:7], v[64:65], s[0:1], v[6:7] op_sel_hi:[1,0,1]
	v_pk_fma_f32 v[8:9], v[66:67], s[10:11], v[8:9] op_sel_hi:[1,0,1]
	v_pk_fma_f32 v[6:7], v[68:69], s[10:11], v[6:7] op_sel_hi:[1,0,1]
	v_pk_fma_f32 v[8:9], v[70:71], s[20:21], v[8:9] op_sel_hi:[1,0,1]
	v_pk_fma_f32 v[6:7], v[72:73], s[20:21], v[6:7] op_sel_hi:[1,0,1]
	v_pk_fma_f32 v[8:9], v[74:75], s[28:29], v[8:9] op_sel_hi:[1,0,1]
	v_pk_fma_f32 v[6:7], v[76:77], s[28:29], v[6:7] op_sel_hi:[1,0,1]
	v_readlane_b32 s0, v4, 52
	v_readlane_b32 s10, v4, 53
	v_readlane_b32 s20, v4, 54
	v_readlane_b32 s28, v4, 55
	v_pk_fma_f32 v[8:9], v[78:79], s[0:1], v[8:9] op_sel_hi:[1,0,1]
	v_pk_fma_f32 v[6:7], v[80:81], s[0:1], v[6:7] op_sel_hi:[1,0,1]
	v_pk_fma_f32 v[8:9], v[82:83], s[10:11], v[8:9] op_sel_hi:[1,0,1]
	v_pk_fma_f32 v[6:7], v[84:85], s[10:11], v[6:7] op_sel_hi:[1,0,1]
	v_pk_fma_f32 v[8:9], v[86:87], s[20:21], v[8:9] op_sel_hi:[1,0,1]
	v_pk_fma_f32 v[6:7], v[88:89], s[20:21], v[6:7] op_sel_hi:[1,0,1]
	v_pk_fma_f32 v[8:9], v[90:91], s[28:29], v[8:9] op_sel_hi:[1,0,1]
	v_pk_fma_f32 v[6:7], v[92:93], s[28:29], v[6:7] op_sel_hi:[1,0,1]
	s_waitcnt lgkmcnt(0)
	v_readlane_b32 s0, v4, 56
	v_readlane_b32 s10, v4, 57
	v_readlane_b32 s20, v4, 58
	v_readlane_b32 s28, v4, 59
	v_pk_fma_f32 v[8:9], v[94:95], s[0:1], v[8:9] op_sel_hi:[1,0,1]
	v_pk_fma_f32 v[6:7], v[96:97], s[0:1], v[6:7] op_sel_hi:[1,0,1]
	v_pk_fma_f32 v[8:9], v[98:99], s[10:11], v[8:9] op_sel_hi:[1,0,1]
	v_pk_fma_f32 v[6:7], v[100:101], s[10:11], v[6:7] op_sel_hi:[1,0,1]
	v_pk_fma_f32 v[8:9], v[102:103], s[20:21], v[8:9] op_sel_hi:[1,0,1]
	v_pk_fma_f32 v[6:7], v[104:105], s[20:21], v[6:7] op_sel_hi:[1,0,1]
	v_pk_fma_f32 v[8:9], v[106:107], s[28:29], v[8:9] op_sel_hi:[1,0,1]
	v_pk_fma_f32 v[6:7], v[108:109], s[28:29], v[6:7] op_sel_hi:[1,0,1]
	v_readlane_b32 s0, v4, 60
	v_readlane_b32 s10, v4, 61
	v_readlane_b32 s20, v4, 62
	v_readlane_b32 s28, v4, 63
	v_pk_fma_f32 v[8:9], v[110:111], s[0:1], v[8:9] op_sel_hi:[1,0,1]
	v_pk_fma_f32 v[6:7], v[112:113], s[0:1], v[6:7] op_sel_hi:[1,0,1]
	v_pk_fma_f32 v[8:9], v[114:115], s[10:11], v[8:9] op_sel_hi:[1,0,1]
	v_pk_fma_f32 v[6:7], v[116:117], s[10:11], v[6:7] op_sel_hi:[1,0,1]
	v_pk_fma_f32 v[8:9], v[118:119], s[20:21], v[8:9] op_sel_hi:[1,0,1]
	v_pk_fma_f32 v[6:7], v[120:121], s[20:21], v[6:7] op_sel_hi:[1,0,1]
	v_pk_fma_f32 v[8:9], v[122:123], s[28:29], v[8:9] op_sel_hi:[1,0,1]
	v_pk_fma_f32 v[6:7], v[124:125], s[28:29], v[6:7] op_sel_hi:[1,0,1]
	v_readlane_b32 s16, v255, 3
	v_mul_f32_e64 v29, |v21|, v27
	v_mul_f32_e64 v30, |v22|, v27
	v_mul_f32_e64 v31, |v23|, v27
	v_mul_f32_e64 v32, |v17|, v27
	v_mul_f32_e32 v29, 0xbfb8aa3b, v29
	v_mul_f32_e32 v30, 0xbfb8aa3b, v30
	v_mul_f32_e32 v31, 0xbfb8aa3b, v31
	v_mul_f32_e32 v32, 0xbfb8aa3b, v32
	v_exp_f32_e32 v29, v29
	v_exp_f32_e32 v30, v30
	v_exp_f32_e32 v31, v31
	v_exp_f32_e32 v32, v32
	s_sub_i32 s0, s22, s16
	s_cmp_gt_u32 s16, 3
	s_cselect_b32 s1, 1, 0
	s_sub_i32 s10, s23, s0
	s_add_i32 s10, s10, -7
	s_add_i32 s11, s23, s0
	s_and_b64 s[28:29], s[18:19], exec
	s_cselect_b32 s10, s11, s10
	s_sub_i32 s10, s10, s1
	s_lshl_b32 s10, s10, 1
	s_and_b64 s[28:29], s[8:9], exec
	s_mov_b32 s11, 0xc10000
	s_cselect_b32 s11, s11, 0x400000
	s_mov_b32 s20, 0x1e510000
	s_cselect_b32 s20, s20, 0x1dd00000
	s_movk_i32 s46, 0x2040
	s_cselect_b32 s46, 0x1040, s46
	s_cmp_eq_u32 s1, 0
	s_cselect_b32 s11, s11, s20
	s_add_u32 s20, s14, s11
	s_addc_u32 s21, s15, 0
	s_add_u32 s20, s20, s10
	s_addc_u32 s21, s21, 0
	v_mul_f32_e32 v8, v29, v8
	v_mul_f32_e32 v9, v30, v9
	v_mul_f32_e32 v6, v31, v6
	v_mul_f32_e32 v7, v32, v7
	v_cvt_pk_bf16_f32 v8, v8, v8
	v_cvt_pk_bf16_f32 v9, v9, v9
	v_cvt_pk_bf16_f32 v6, v6, v6
	v_cvt_pk_bf16_f32 v7, v7, v7
	ds_write_b16 v40, v8
	ds_write_b16 v40, v9 offset:16
	ds_write_b16 v40, v6 offset:32
	ds_write_b16 v40, v7 offset:48
	s_waitcnt lgkmcnt(0)
	s_barrier
	ds_read_b128 v[44:47], v41
	v_xor_b32_e32 v40, 0x1000, v40
	v_mul_u32_u24_e32 v48, s46, v42
	v_mov_b32_e32 v49, 0
	v_lshlrev_b32_e32 v48, 1, v48
	v_xor_b32_e32 v41, 0x1000, v41
	s_and_b64 s[28:29], s[18:19], exec
	s_cselect_b32 s11, 1, 0
	s_cmp_eq_u32 s0, 0
	s_cselect_b32 s11, s11, 0
	v_lshl_add_u64 v[48:49], s[20:21], 0, v[48:49]
	s_cmp_lg_u32 s11, 0
	s_waitcnt lgkmcnt(0)
	s_cbranch_scc1 .Lfg_special_p0
	global_store_dwordx4 v[48:49], v[44:47], off
	s_branch .LBB0_53

.LBB0_1071:
	v_readlane_b32 s4, v255, 1
	s_add_i32 s26, s75, 15
	v_readlane_b32 s5, v255, 2
	s_cmp_lt_i32 s26, s5
	s_cselect_b64 s[4:5], -1, 0
	s_and_b64 s[2:3], s[2:3], s[4:5]
	s_andn2_b64 vcc, exec, s[2:3]
	s_branch .LBB0_1125
	s_mov_b64 s[6:7], s[84:85]
	v_mov_b32_e32 v0, v213
	s_waitcnt vmcnt(0)
	s_waitcnt vmcnt(0)
	v_cmp_eq_u32_e32 vcc, 0, v0
	s_barrier
	s_and_saveexec_b64 s[2:3], vcc
	s_cbranch_execz .LBB0_1124
	v_readlane_b32 s9, v255, 4
	s_load_dwordx2 s[6:7], s[6:7], 0xf0
	s_getreg_b32 s8, hwreg(HW_REG_XCC_ID, 0, 4)
	v_mov_b32_e32 v0, s9
	s_waitcnt vmcnt(0) expcnt(0) lgkmcnt(0)
	ds_read_b32 v2, v0
	v_readlane_b32 s9, v255, 5
	s_and_b32 s22, s8, 15
	s_waitcnt lgkmcnt(0)
	v_cmp_ne_u32_e32 vcc, 0, v2
	v_mov_b32_e32 v0, s9
	ds_read_b32 v0, v0
	s_cbranch_vccnz .LBB0_1088
	s_add_u32 s8, s6, 0x1000
	s_addc_u32 s9, s7, 0
	s_add_u32 s10, s6, 0x1100
	s_addc_u32 s11, s7, 0
	s_add_u32 s12, s6, 0x1200
	s_addc_u32 s13, s7, 0
	s_add_u32 s14, s6, 0x1300
	s_addc_u32 s15, s7, 0
	s_mov_b32 s23, 1
	s_branch .LBB0_1076

.LBB0_1125:
	v_readlane_b32 s2, v255, 1
	v_readlane_b32 s3, v255, 2
	s_cmp_ge_i32 s26, s2
	s_cselect_b64 s[2:3], -1, 0
	s_and_b64 s[2:3], s[2:3], s[4:5]
	s_andn2_b64 vcc, exec, s[2:3]
	s_cbranch_vccnz .LBB0_1160
	s_mov_b64 s[2:3], s[84:85]
	s_load_dwordx4 s[4:7], s[2:3], 0xe8
	s_mov_b32 s33, s81
	v_readlane_b32 s2, v255, 0
	s_mov_b32 s38, s83
	v_readlane_b32 s3, v255, 3
	s_waitcnt lgkmcnt(0)
	s_add_u32 s39, s4, 0x4600000
	s_addc_u32 s40, s5, 0
	s_add_u32 s41, s6, 0xbd00000
	s_addc_u32 s46, s7, 0
	v_lshl_add_u32 v8, s3, 6, v249
	v_mov_b32_e32 v0, v8
	s_cmpk_lt_i32 s38, 0x200
	s_cselect_b64 s[2:3], -1, 0
	s_cmpk_gt_i32 s38, 0x1ff
	v_readfirstlane_b32 s8, v8
	s_cbranch_scc1 .LBB0_1128
	s_and_b32 s16, s38, 7
	s_lshl_b32 s16, s16, 6
	s_lshr_b32 s17, s38, 3
	s_add_i32 s16, s16, s17
	s_bfe_u32 s59, s16, 0x20003
	s_lshr_b32 s17, s16, 5
	s_lshl_b32 s17, s17, 3
	s_and_b32 s16, s16, 7
	s_add_i32 s16, s17, s16
	s_lshl_b32 s4, s16, 8
	s_addk_i32 s4, 0xc000
	s_lshr_b32 s4, s4, 11
	s_ashr_i32 s5, s16, 4
	s_add_i32 s4, s4, 4
	s_cmp_lt_i32 s16, 64
	s_cselect_b32 s4, s5, s4
	s_ashr_i32 s17, s16, 31
	s_lshl_b32 s9, s59, 9
	s_lshl_b64 s[10:11], s[16:17], 19
	s_add_u32 s5, s41, s10
	s_addc_u32 s10, s46, s11
	s_add_u32 s18, s5, s9
	s_addc_u32 s19, s10, 0
	s_ashr_i32 s5, s4, 31
	s_lshl_b64 s[4:5], s[4:5], 19
	s_add_u32 s4, s39, s4
	s_addc_u32 s5, s40, s5
	s_add_u32 s20, s4, s9
	s_addc_u32 s21, s5, 0

; template <class Epi, class Sched>
; DI void gemm_phase(int wave_, LAS unsigned char* lds, LAS unsigned char* lx, const GemmP g, const Sched& S, const Epi& E) {
;     ...
;         const bool has_next = S.next(ui + 1, nxt);
;         const char* nA = has_next ? nxt.A : cA; const char* nB = has_next ? nxt.B : cB;
.LBB0_1134:
	s_add_i32 s57, s57, 1
	s_mul_i32 s9, s57, s33
	s_add_i32 s9, s9, s38
	s_cmpk_lt_i32 s9, 0x200
	s_cselect_b64 s[14:15], -1, 0
	s_cmpk_gt_i32 s9, 0x1ff
	s_cbranch_scc1 .LBB0_1136
	s_and_b32 s8, s9, 7
	s_lshl_b32 s8, s8, 6
	s_lshr_b32 s10, s9, 3
	s_add_i32 s8, s8, s10
	s_bfe_u32 s58, s8, 0x20003
	s_lshr_b32 s10, s8, 5
	s_lshl_b32 s10, s10, 3
	s_and_b32 s8, s8, 7
	s_add_i32 s8, s10, s8
	s_lshl_b32 s10, s8, 8
	s_addk_i32 s10, 0xc000
	s_lshr_b32 s10, s10, 11
	s_ashr_i32 s9, s8, 4
	s_add_i32 s10, s10, 4
	s_cmp_lt_i32 s8, 64
	s_cselect_b32 s12, s9, s10
	s_ashr_i32 s9, s8, 31
	s_lshl_b32 s17, s58, 9
	s_lshl_b64 s[10:11], s[8:9], 19
	s_add_u32 s9, s41, s10
	s_addc_u32 s11, s46, s11
	s_add_u32 s10, s9, s17
	s_addc_u32 s11, s11, 0
	s_ashr_i32 s13, s12, 31
	s_lshl_b64 s[12:13], s[12:13], 19
	s_add_u32 s9, s39, s12
	s_addc_u32 s13, s40, s13
	s_add_u32 s12, s9, s17
	s_addc_u32 s13, s13, 0

.LBB0_1160:
	s_add_i32 s26, s75, 16
	v_readlane_b32 s2, v255, 1
	v_readlane_b32 s3, v255, 2
	s_cmp_gt_i32 s26, s2
	s_cselect_b64 s[4:5], -1, 0
	s_cmp_lt_i32 s26, s3
	s_cselect_b64 s[2:3], -1, 0
	s_and_b64 s[4:5], s[4:5], s[2:3]
	s_andn2_b64 vcc, exec, s[4:5]
	s_branch .LBB0_1214
	s_mov_b64 s[6:7], s[84:85]
	v_mov_b32_e32 v0, v213
	s_waitcnt vmcnt(0)
	s_waitcnt vmcnt(0)
	v_cmp_eq_u32_e32 vcc, 0, v0
	s_barrier
	s_and_saveexec_b64 s[4:5], vcc
	s_cbranch_execz .LBB0_1213
	v_readlane_b32 s9, v255, 4
	s_load_dwordx2 s[6:7], s[6:7], 0xf0
	s_getreg_b32 s8, hwreg(HW_REG_XCC_ID, 0, 4)
	v_mov_b32_e32 v0, s9
	s_waitcnt vmcnt(0) expcnt(0) lgkmcnt(0)
	ds_read_b32 v2, v0
	v_readlane_b32 s9, v255, 5
	s_and_b32 s22, s8, 15
	s_waitcnt lgkmcnt(0)
	v_cmp_ne_u32_e32 vcc, 0, v2
	v_mov_b32_e32 v0, s9
	ds_read_b32 v0, v0
	s_cbranch_vccnz .LBB0_1177
	s_add_u32 s8, s6, 0x1000
	s_addc_u32 s9, s7, 0
	s_add_u32 s10, s6, 0x1100
	s_addc_u32 s11, s7, 0
	s_add_u32 s12, s6, 0x1200
	s_addc_u32 s13, s7, 0
	s_add_u32 s14, s6, 0x1300
	s_addc_u32 s15, s7, 0
	s_mov_b32 s23, 1
	s_branch .LBB0_1165

; DI int opaque_tid(int wave) { int t = wave * 64 + (int)__builtin_amdgcn_mbcnt_hi(~0u, __builtin_amdgcn_mbcnt_lo(~0u, 0u)); asm volatile("" : "+v"(t)); return t; }
; #define PG8_STAGE(bufoff, gbase, voff) do { _Pragma("unroll") for (int _i = 0; _i < 2; ++_i) \
;         __builtin_amdgcn_global_load_lds((const unsigned*)((const char*)(gbase) + (voff)[_i]), (LAS unsigned*)(lds + (bufoff) + ldsw + _i * 8192), 16, 0, 0); } while (0)
; #define PG8_WAIT_V(n) asm volatile("s_waitcnt vmcnt(" #n ")" ::: "memory")
; #define PG8_BAR __builtin_amdgcn_s_barrier()
; template <class Epi, class Sched>
; DI void gemm_phase(int wave_, LAS unsigned char* lds, LAS unsigned char* lx, const GemmP g, const Sched& S, const Epi& E) {
;     const int tid = opaque_tid(wave_), wid = __builtin_amdgcn_readfirstlane(tid >> 6), lane = tid & 63, wr = wid >> 2, wc = wid & 3, fr = lane & 15, fq = lane >> 4;
;     const int K = g.K, nt = K / BK;
;     unsigned voffA[2], voffB[2];
; #pragma unroll
;     for (int i = 0; i < 2; ++i) { int R, C; stage_rc(tid * 16 + i * 8192, R, C); const int Rb = (R & ~31) + perm32(R & 31);
;         voffA[i] = (unsigned)(R * g.lda + C) * 2u; voffB[i] = (unsigned)(Rb * g.ldb + C) * 2u; }
;     const size_t kstep = (size_t)(BK * 2);
;     const size_t hstepA = (size_t)HALF * g.lda * 2, hstepB = (size_t)HALF * g.ldb * 2;
;     const unsigned ldsw = (unsigned)wid * 1024u;
;     const int aoff = lds_byte(wr * 64 + fr, fq * 8), boff = lds_byte(wc * 32 + fr, fq * 8);
;     ...
;     Unit cur, nxt; int ui = 0;
;     if (!S.next(0, cur)) return;
;     f32x4 acc[2][2][4][2];
; #pragma unroll
;     for (int a = 0; a < 2; ++a)
; #pragma unroll
;         for (int b = 0; b < 2; ++b)
; #pragma unroll
;             for (int m = 0; m < 4; ++m)
; #pragma unroll
;                 for (int n = 0; n < 2; ++n) acc[a][b][m][n] = (f32x4){0.f, 0.f, 0.f, 0.f};
;     bf16x8 At[4][2], B0[2][2], B1[2][2];
;     const char* cA = cur.A; const char* cB = cur.B;
;     PG8_STAGE(PG8_SB(0, 0), cB, voffB); PG8_STAGE(PG8_SB(0, 1), cB + hstepB, voffB); PG8_STAGE(PG8_SA(0, 0), cA, voffA); PG8_STAGE(PG8_SA(0, 1), cA + hstepA, voffA);
;     if (wr == 1) PG8_BAR;
;     PG8_WAIT_V(2); PG8_BAR;
;     PG8_STAGE(PG8_SB(1, 0), cB + kstep, voffB); PG8_STAGE(PG8_SA(1, 0), cA + kstep, voffA); PG8_STAGE(PG8_SB(1, 1), cB + hstepB + kstep, voffB);
.LBB0_1214:
	v_readlane_b32 s4, v255, 1
	v_readlane_b32 s5, v255, 2
	s_cmp_ge_i32 s26, s4
	s_cselect_b64 s[4:5], -1, 0
	s_and_b64 s[2:3], s[4:5], s[2:3]
	s_andn2_b64 vcc, exec, s[2:3]
	s_cbranch_vccnz .LBB0_1231
	s_mov_b64 s[2:3], s[84:85]
	s_mov_b32 s33, s81
	v_readlane_b32 s4, v255, 0
	s_mov_b32 s38, s83
	v_readlane_b32 s5, v255, 3
	s_cmpk_gt_i32 s38, 0x1ff
	s_nop 0
	v_lshl_add_u32 v8, s5, 6, v249
	v_mov_b32_e32 v0, v8
	s_nop 0
	v_readfirstlane_b32 s8, v8
	s_cbranch_scc1 .LBB0_1231
	v_lshlrev_b32_e32 v0, 4, v8
	v_add_u32_e32 v1, 0x2000, v0
	v_ashrrev_i32_e32 v2, 31, v1
	v_lshrrev_b32_e32 v2, 22, v2
	v_add_u32_e32 v2, v1, v2
	v_ashrrev_i32_e32 v2, 10, v2
	v_mul_i32_i24_e32 v3, 0x400, v2
	v_sub_u32_e32 v1, v1, v3
	v_lshrrev_b32_e32 v3, 4, v1
	v_bitop3_b32 v1, v3, v1, 32 bitop3:0x6c
	v_ashrrev_i32_e32 v3, 31, v1
	v_lshrrev_b32_e32 v3, 26, v3
	v_add_u32_e32 v3, v1, v3
	v_lshlrev_b32_e32 v5, 3, v2
	v_ashrrev_i32_e32 v4, 6, v3
	v_and_b32_e32 v5, -16, v5
	v_and_b32_e32 v3, 0xc0, v3
	v_add_u32_e32 v5, v4, v5
	v_sub_u32_e32 v1, v1, v3
	s_load_dwordx4 s[4:7], s[2:3], 0xe8
	v_and_b32_e32 v4, 3, v4
	s_mov_b32 s2, 0x7fffe0
	v_lshrrev_b32_e32 v6, 2, v5
	v_lshlrev_b32_e32 v7, 1, v5
	v_lshlrev_b32_e32 v2, 5, v2
	v_ashrrev_i16_sdwa v1, v216, sext(v1) dst_sel:DWORD dst_unused:UNUSED_PAD src0_sel:DWORD src1_sel:BYTE_0
	v_and_or_b32 v4, v5, s2, v4
	v_and_b32_e32 v6, 4, v6
	v_and_b32_e32 v7, 24, v7
	v_and_b32_e32 v2, 32, v2
	v_bfe_i32 v1, v1, 0, 16
	v_or3_b32 v4, v4, v6, v7
	v_add_lshl_u32 v1, v2, v1, 1
	v_lshl_add_u32 v128, v4, 9, v1
	v_lshl_add_u32 v130, v5, 11, v1
	v_bfe_i32 v1, v8, 27, 1
	v_lshrrev_b32_e32 v1, 22, v1
	v_add_u32_e32 v1, v0, v1
	v_and_b32_e32 v1, 0xfffffc00, v1
	v_sub_u32_e32 v0, v0, v1
	v_ashrrev_i32_e32 v2, 31, v8
	v_lshrrev_b32_e32 v1, 4, v0
	v_lshrrev_b32_e32 v2, 26, v2
	v_bitop3_b32 v1, v1, v0, 32 bitop3:0x6c
	v_ashrrev_i32_e32 v0, 31, v0
	v_add_u32_e32 v2, v8, v2
	s_waitcnt lgkmcnt(0)
	s_add_u32 s39, s4, 0x4c00000
	v_lshrrev_b32_e32 v0, 26, v0
	v_ashrrev_i32_e32 v2, 6, v2
	s_addc_u32 s40, s5, 0
	v_add_u32_e32 v0, v1, v0
	v_lshlrev_b32_e32 v3, 3, v2
	s_add_u32 s41, s6, 0xfd00000
	v_ashrrev_i32_e32 v0, 6, v0
	v_and_b32_e32 v3, -16, v3
	s_addc_u32 s44, s7, 0
	v_add_u32_e32 v3, v0, v3
	v_and_b32_e32 v4, 3, v0
	s_and_b32 s16, s38, 7
	s_lshl_b32 s16, s16, 6
	s_lshr_b32 s17, s38, 3
	s_add_i32 s16, s16, s17
	s_bfe_u32 s57, s16, 0x20003
	s_lshr_b32 s17, s16, 5
	s_lshl_b32 s17, s17, 3
	s_and_b32 s16, s16, 7
	s_add_i32 s16, s17, s16
	v_and_or_b32 v4, v3, s2, v4
	s_lshl_b32 s2, s16, 8
	s_addk_i32 s2, 0xc000
	s_ashr_i32 s9, s8, 6
	s_lshr_b32 s2, s2, 11
	s_ashr_i32 s10, s8, 8
	s_lshl_b32 s46, s9, 10
	s_lshr_b32 s3, s16, 4
	s_add_i32 s2, s2, 4
	s_cmp_lt_i32 s16, 64
	s_cselect_b32 s4, s3, s2
	s_ashr_i32 s17, s16, 31
	s_lshl_b32 s5, s57, 8
	s_lshl_b64 s[2:3], s[16:17], 19
	s_lshl_b32 s11, s57, 9
	s_add_u32 s2, s41, s2
	s_addc_u32 s3, s44, s3
	s_add_u32 s18, s2, s11
	s_addc_u32 s19, s3, 0
	s_lshl_b32 s2, s4, 10
	v_mul_i32_i24_e32 v0, 64, v0
	s_or_b32 s2, s2, s5
	v_sub_u32_e32 v0, v1, v0
	s_ashr_i32 s3, s2, 31
	v_lshrrev_b32_e32 v5, 2, v3
	v_lshlrev_b32_e32 v6, 1, v3
	v_lshlrev_b32_e32 v2, 5, v2
	v_ashrrev_i16_sdwa v0, v216, sext(v0) dst_sel:DWORD dst_unused:UNUSED_PAD src0_sel:DWORD src1_sel:BYTE_0
	s_lshl_b64 s[2:3], s[2:3], 9
	v_and_b32_e32 v5, 4, v5
	v_and_b32_e32 v6, 24, v6
	v_and_b32_e32 v2, 32, v2
	v_bfe_i32 v0, v0, 0, 16
	s_add_u32 s20, s39, s2
	v_or3_b32 v4, v4, v5, v6
	v_add_lshl_u32 v0, v2, v0, 1
	s_addc_u32 s21, s40, s3
	s_add_i32 s47, s46, 0
	v_lshl_add_u32 v176, v4, 9, v0
	s_add_i32 m0, s47, 0x10000
	v_lshl_add_u32 v132, v3, 11, v0
	global_load_lds_dwordx4 v176, s[20:21]
	s_add_i32 m0, s47, 0x12000
	s_add_u32 s2, s20, 0x10000
	global_load_lds_dwordx4 v128, s[20:21]
	s_addc_u32 s3, s21, 0
	s_add_i32 m0, s47, 0x14000
	s_add_i32 s48, s47, 0x2000
	global_load_lds_dwordx4 v176, s[2:3]
	s_add_i32 m0, s47, 0x16000
	v_mov_b32_e32 v129, v177
	global_load_lds_dwordx4 v128, s[2:3]
	s_mov_b32 m0, s47
	s_add_u32 s2, s18, 0x40000
	global_load_lds_dwordx4 v132, s[18:19]
	s_mov_b32 m0, s48
	s_addc_u32 s3, s19, 0
	s_add_i32 s49, s47, 0x4000
	global_load_lds_dwordx4 v130, s[18:19]
	s_mov_b32 m0, s49
	s_add_i32 s50, s47, 0x6000
	global_load_lds_dwordx4 v132, s[2:3]
	s_mov_b32 m0, s50
	v_mov_b32_e32 v133, v177
	global_load_lds_dwordx4 v130, s[2:3]
	v_mov_b32_e32 v131, v177
	s_cmp_eq_u32 s10, 1
	v_lshl_add_u64 v[6:7], s[20:21], 0, v[176:177]
	v_lshl_add_u64 v[4:5], s[20:21], 0, v[128:129]
	v_lshl_add_u64 v[0:1], s[18:19], 0, v[132:133]
	s_cselect_b64 s[2:3], -1, 0
	s_cmp_lg_u32 s10, 1
	v_lshl_add_u64 v[2:3], s[18:19], 0, v[130:131]
	s_cbranch_scc1 .LBB0_1218
	s_barrier

.LBB0_1221:
	s_add_i32 s55, s55, 1
	s_mul_i32 s9, s55, s33
	s_add_i32 s9, s9, s38
	s_cmpk_lt_i32 s9, 0x200
	s_cselect_b64 s[14:15], -1, 0
	s_cmpk_gt_i32 s9, 0x1ff
	s_cbranch_scc1 .LBB0_1223
	s_and_b32 s8, s9, 7
	s_lshl_b32 s8, s8, 6
	s_lshr_b32 s10, s9, 3
	s_add_i32 s8, s8, s10
	s_bfe_u32 s56, s8, 0x20003
	s_lshr_b32 s10, s8, 5
	s_lshl_b32 s10, s10, 3
	s_and_b32 s8, s8, 7
	s_add_i32 s8, s10, s8
	s_lshl_b32 s10, s8, 8
	s_addk_i32 s10, 0xc000
	s_lshr_b32 s10, s10, 11
	s_lshr_b32 s9, s8, 4
	s_add_i32 s10, s10, 4
	s_cmp_lt_i32 s8, 64
	s_cselect_b32 s12, s9, s10
	s_ashr_i32 s9, s8, 31
	s_lshl_b32 s13, s56, 8
	s_lshl_b64 s[10:11], s[8:9], 19
	s_lshl_b32 s9, s56, 9
	s_add_u32 s10, s41, s10
	s_addc_u32 s11, s44, s11
	s_add_u32 s10, s10, s9
	s_addc_u32 s11, s11, 0
	s_lshl_b32 s9, s12, 10
	s_or_b32 s12, s9, s13
	s_ashr_i32 s13, s12, 31
	s_lshl_b64 s[12:13], s[12:13], 9
	s_add_u32 s12, s39, s12
	s_addc_u32 s13, s40, s13

; DI void filter_gen(const Inputs& in, int l, unsigned char* ws, LAS unsigned char* lds, int vcu, int G, int wave, int tid) {
;     ...
;     for (int it = wgi * 8 + wave; it < 4096 + 2048; it += nwg * 8) {
;         const int g = it >= 4096, t = g ? it - 4096 : it, L = g ? 2048 : 4096, FRS = g ? FRS1 : FRS0;
;         bf16_t* FR = (bf16_t*)(ws + (g ? WS_FR1 : WS_FR0)); bf16_t* FRO = (bf16_t*)(ws + (g ? WS_FRO1 : WS_FRO0));
;         const float tl = (float)t / (float)(L - 1);
;         const float w = 6.2831853071795864769f * (float)t / (float)L;
;         float z;
;         { const int k = lane; const int fi = (k >= 17) ? k - 17 : k - 1; const float f = 1e-4f + (float)fi * ((15.0f - 1e-4f) / 15.0f);
;           z = (k == 0) ? tl : (k <= 16 ? __cosf(f * w) : -__sinf(f * w)); if (k > 32) z = 0.f; }
;         float a = Bs[lane];
; #pragma unroll 11
;         for (int k = 0; k < 33; ++k) a += __shfl(z, k) * W1s[k * 64 + lane];
;         const float h1 = __sinf(a);
;         a = Bs[64 + lane];
; #pragma unroll 16
;         for (int k = 0; k < 64; ++k) a += __shfl(h1, k) * W2s[k * 64 + lane];
;         const float h2 = __sinf(a);
;         float o[4] = {0.f, 0.f, 0.f, 0.f};
; #pragma unroll 16
;         for (int k = 0; k < 64; ++k) { const float hk = __shfl(h2, k);
; #pragma unroll
;             for (int q = 0; q < 4; ++q) o[q] += hk * W3s[k * 256 + lane + 64 * q]; }
; #pragma unroll
;         for (int q = 0; q < 4; ++q) {
;             const int cidx = 256 * chunk + lane + 64 * q, dir = cidx >> 9, c = cidx & 511;
;             const float delta = fabsf(-3.0701134573253942f + (float)c * ((-15.350567286626972f + 3.0701134573253942f) / 511.0f));
;             const float val = o[q] * __expf(-tl * delta);
;             bf16_t* row = FR + (size_t)c * FRS; bf16_t* rowo = FRO + (size_t)c * FRS;
.LBB0_1631:
	s_or_b64 exec, exec, s[2:3]
	s_lshl_b32 s2, s58, 1
	s_and_b32 s2, s2, -8
	s_add_i32 s22, s2, s59
	s_cmpk_gt_i32 s22, 0x17ff
	s_waitcnt lgkmcnt(0)
	s_barrier
	s_cbranch_scc1 .LBB0_1670
	v_not_b32_e32 v0, 16
	v_cmp_lt_u32_e64 s[2:3], 16, v110
	s_lshl_b32 s8, s16, 8
	v_lshlrev_b32_e32 v2, 2, v110
	v_cndmask_b32_e64 v0, -1, v0, s[2:3]
	v_add_u32_e32 v0, v0, v110
	v_cvt_f32_i32_e32 v0, v0
	s_and_b32 s8, s8, 0x100
	v_mov_b32_e32 v1, 0x38d1b717
	v_add_u32_e32 v43, 0, v2
	v_or_b32_e32 v44, s8, v2
	v_fmamk_f32 v42, v0, 0x3f7fff90, v1
	v_add_u32_e32 v0, 0x16100, v43
	v_or_b32_e32 v45, 1, v44
	v_or_b32_e32 v46, 2, v44
	v_or_b32_e32 v47, 3, v44
	s_sub_i32 s4, s33, s16
	ds_read2st64_b32 v[0:1], v0 offset1:1
	v_cvt_f32_u32_e32 v3, v44
	v_cvt_f32_u32_e32 v4, v45
	v_cvt_f32_u32_e32 v5, v46
	v_cvt_f32_u32_e32 v6, v47
	s_lshl_b32 s9, s4, 1
	s_cmp_gt_u32 s16, 1
	s_cselect_b64 s[12:13], -1, 0
	s_add_i32 s9, s9, 6
	v_mov_b32_e32 v7, 0xc0447cbd
	s_add_i32 s8, 0, 0x12100
	v_cmp_ne_u32_e64 s[4:5], 0, v110
	v_cmp_lt_u32_e64 s[6:7], 32, v110
	s_and_b32 s23, s9, -8
	v_fmamk_f32 v48, v3, 0xbcc4df2d, v7
	v_fmamk_f32 v49, v4, 0xbcc4df2d, v7
	v_fmamk_f32 v50, v5, 0xbcc4df2d, v7
	v_fmamk_f32 v51, v6, 0xbcc4df2d, v7
	v_add_u32_e32 v52, s8, v2
	s_lshr_b32 s8, s16, 1
	s_sub_i32 s9, 7, s59
	s_cmp_eq_u32 s8, 0
	s_cselect_b32 s9, s9, s59
	s_lshl_b32 s9, s9, 1
	s_add_i32 s9, s9, 0x18000
	s_and_b32 s10, s59, 3
	s_lshl_b32 s11, s10, 6
	s_lshl_b32 s10, s10, 10
	s_add_i32 s10, s10, 0x18000
	s_and_b32 s8, s16, 1
	s_lshl_b32 s8, s8, 8
	s_add_i32 s8, s8, s11
	v_lshl_add_u32 v100, v249, 6, s9
	v_lshl_add_u32 v101, v249, 4, s10
	v_add_u32_e32 v102, s8, v249
	v_lshlrev_b32_e32 v103, 4, v249
	s_branch .LBB0_1634

; DI void filter_gen(const Inputs& in, int l, unsigned char* ws, LAS unsigned char* lds, int vcu, int G, int wave, int tid) {
;     ...
;         float a = Bs[lane];
; #pragma unroll 11
;         for (int k = 0; k < 33; ++k) a += __shfl(z, k) * W1s[k * 64 + lane];
;         const float h1 = __sinf(a);
;         a = Bs[64 + lane];
; #pragma unroll 16
;         for (int k = 0; k < 64; ++k) a += __shfl(h1, k) * W2s[k * 64 + lane];
;         const float h2 = __sinf(a);
.LBB0_1640:
	s_or_b64 exec, exec, s[10:11]
	v_cndmask_b32_e64 v2, v2, 0, s[6:7]
	s_waitcnt lgkmcnt(0)
	v_add_u32_e32 v3, 0x10000, v43
	ds_read2st64_b32 v[56:57], v3 offset0:0 offset1:1
	ds_read2st64_b32 v[58:59], v3 offset0:2 offset1:3
	ds_read2st64_b32 v[60:61], v3 offset0:4 offset1:5
	ds_read2st64_b32 v[62:63], v3 offset0:6 offset1:7
	ds_read2st64_b32 v[64:65], v3 offset0:8 offset1:9
	ds_read2st64_b32 v[66:67], v3 offset0:10 offset1:11
	ds_read2st64_b32 v[68:69], v3 offset0:12 offset1:13
	ds_read2st64_b32 v[70:71], v3 offset0:14 offset1:15
	ds_read2st64_b32 v[72:73], v3 offset0:16 offset1:17
	ds_read2st64_b32 v[74:75], v3 offset0:18 offset1:19
	ds_read2st64_b32 v[76:77], v3 offset0:20 offset1:21
	ds_read2st64_b32 v[78:79], v3 offset0:22 offset1:23
	ds_read2st64_b32 v[80:81], v3 offset0:24 offset1:25
	ds_read2st64_b32 v[82:83], v3 offset0:26 offset1:27
	ds_read2st64_b32 v[84:85], v3 offset0:28 offset1:29
	ds_read2st64_b32 v[86:87], v3 offset0:30 offset1:31
	ds_read_b32 v38, v3 offset:8192
	v_mov_b32_e32 v4, v0
	s_waitcnt lgkmcnt(8)
	v_readlane_b32 s10, v2, 0
	v_readlane_b32 s14, v2, 1
	v_readlane_b32 s16, v2, 2
	v_readlane_b32 s20, v2, 3
	v_fmac_f32_e32 v4, s10, v56
	v_fmac_f32_e32 v4, s14, v57
	v_fmac_f32_e32 v4, s16, v58
	v_fmac_f32_e32 v4, s20, v59
	v_readlane_b32 s10, v2, 4
	v_readlane_b32 s14, v2, 5
	v_readlane_b32 s16, v2, 6
	v_readlane_b32 s20, v2, 7
	v_fmac_f32_e32 v4, s10, v60
	v_fmac_f32_e32 v4, s14, v61
	v_fmac_f32_e32 v4, s16, v62
	v_fmac_f32_e32 v4, s20, v63
	v_readlane_b32 s10, v2, 8
	v_readlane_b32 s14, v2, 9
	v_readlane_b32 s16, v2, 10
	v_readlane_b32 s20, v2, 11
	v_fmac_f32_e32 v4, s10, v64
	v_fmac_f32_e32 v4, s14, v65
	v_fmac_f32_e32 v4, s16, v66
	v_fmac_f32_e32 v4, s20, v67
	v_readlane_b32 s10, v2, 12
	v_readlane_b32 s14, v2, 13
	v_readlane_b32 s16, v2, 14
	v_readlane_b32 s20, v2, 15
	v_fmac_f32_e32 v4, s10, v68
	v_fmac_f32_e32 v4, s14, v69
	v_fmac_f32_e32 v4, s16, v70
	v_fmac_f32_e32 v4, s20, v71
	s_waitcnt lgkmcnt(0)
	v_readlane_b32 s10, v2, 16
	v_readlane_b32 s14, v2, 17
	v_readlane_b32 s16, v2, 18
	v_readlane_b32 s20, v2, 19
	v_fmac_f32_e32 v4, s10, v72
	v_fmac_f32_e32 v4, s14, v73
	v_fmac_f32_e32 v4, s16, v74
	v_fmac_f32_e32 v4, s20, v75
	v_readlane_b32 s10, v2, 20
	v_readlane_b32 s14, v2, 21
	v_readlane_b32 s16, v2, 22
	v_readlane_b32 s20, v2, 23
	v_fmac_f32_e32 v4, s10, v76
	v_fmac_f32_e32 v4, s14, v77
	v_fmac_f32_e32 v4, s16, v78
	v_fmac_f32_e32 v4, s20, v79
	v_readlane_b32 s10, v2, 24
	v_readlane_b32 s14, v2, 25
	v_readlane_b32 s16, v2, 26
	v_readlane_b32 s20, v2, 27
	v_fmac_f32_e32 v4, s10, v80
	v_fmac_f32_e32 v4, s14, v81
	v_fmac_f32_e32 v4, s16, v82
	v_fmac_f32_e32 v4, s20, v83
	v_readlane_b32 s10, v2, 28
	v_readlane_b32 s14, v2, 29
	v_readlane_b32 s16, v2, 30
	v_readlane_b32 s20, v2, 31
	v_fmac_f32_e32 v4, s10, v84
	v_fmac_f32_e32 v4, s14, v85
	v_fmac_f32_e32 v4, s16, v86
	v_fmac_f32_e32 v4, s20, v87
	v_readlane_b32 s10, v2, 32
	s_nop 1
	v_fmac_f32_e32 v4, s10, v38
	v_mul_f32_e32 v2, 0.15915494, v4
	v_sin_f32_e32 v2, v2
	ds_read2st64_b32 v[56:57], v52 offset0:0 offset1:1
	ds_read2st64_b32 v[58:59], v52 offset0:2 offset1:3
	ds_read2st64_b32 v[60:61], v52 offset0:4 offset1:5
	ds_read2st64_b32 v[62:63], v52 offset0:6 offset1:7
	ds_read2st64_b32 v[64:65], v52 offset0:8 offset1:9
	ds_read2st64_b32 v[66:67], v52 offset0:10 offset1:11
	ds_read2st64_b32 v[68:69], v52 offset0:12 offset1:13
	ds_read2st64_b32 v[70:71], v52 offset0:14 offset1:15
	ds_read2st64_b32 v[72:73], v52 offset0:16 offset1:17
	ds_read2st64_b32 v[74:75], v52 offset0:18 offset1:19
	ds_read2st64_b32 v[76:77], v52 offset0:20 offset1:21
	ds_read2st64_b32 v[78:79], v52 offset0:22 offset1:23
	ds_read2st64_b32 v[80:81], v52 offset0:24 offset1:25
	ds_read2st64_b32 v[82:83], v52 offset0:26 offset1:27
	ds_read2st64_b32 v[84:85], v52 offset0:28 offset1:29
	ds_read2st64_b32 v[86:87], v52 offset0:30 offset1:31
	ds_read2st64_b32 v[6:7], v52 offset0:32 offset1:33
	ds_read2st64_b32 v[8:9], v52 offset0:34 offset1:35
	ds_read2st64_b32 v[10:11], v52 offset0:36 offset1:37
	ds_read2st64_b32 v[12:13], v52 offset0:38 offset1:39
	ds_read2st64_b32 v[14:15], v52 offset0:40 offset1:41
	ds_read2st64_b32 v[16:17], v52 offset0:42 offset1:43
	ds_read2st64_b32 v[18:19], v52 offset0:44 offset1:45
	ds_read2st64_b32 v[20:21], v52 offset0:46 offset1:47
	ds_read2st64_b32 v[22:23], v52 offset0:48 offset1:49
	ds_read2st64_b32 v[24:25], v52 offset0:50 offset1:51
	ds_read2st64_b32 v[26:27], v52 offset0:52 offset1:53
	ds_read2st64_b32 v[28:29], v52 offset0:54 offset1:55
	ds_read2st64_b32 v[30:31], v52 offset0:56 offset1:57
	ds_read2st64_b32 v[32:33], v52 offset0:58 offset1:59
	ds_read2st64_b32 v[34:35], v52 offset0:60 offset1:61
	ds_read2st64_b32 v[36:37], v52 offset0:62 offset1:63
	v_mov_b32_e32 v4, v1
	s_waitcnt lgkmcnt(15)
; DI void filter_gen(const Inputs& in, int l, unsigned char* ws, LAS unsigned char* lds, int vcu, int G, int wave, int tid) {
;     ...
;         a = Bs[64 + lane];
; #pragma unroll 16
;         for (int k = 0; k < 64; ++k) a += __shfl(h1, k) * W2s[k * 64 + lane];
;         const float h2 = __sinf(a);
;         float o[4] = {0.f, 0.f, 0.f, 0.f};
; #pragma unroll 16
;         for (int k = 0; k < 64; ++k) { const float hk = __shfl(h2, k);
; #pragma unroll
;             for (int q = 0; q < 4; ++q) o[q] += hk * W3s[k * 256 + lane + 64 * q]; }
	v_readlane_b32 s10, v2, 0
	v_readlane_b32 s14, v2, 1
	v_readlane_b32 s16, v2, 2
	v_readlane_b32 s20, v2, 3
	v_fmac_f32_e32 v4, s10, v56
	v_fmac_f32_e32 v4, s14, v57
	v_fmac_f32_e32 v4, s16, v58
	v_fmac_f32_e32 v4, s20, v59
	v_readlane_b32 s10, v2, 4
	v_readlane_b32 s14, v2, 5
	v_readlane_b32 s16, v2, 6
	v_readlane_b32 s20, v2, 7
	v_fmac_f32_e32 v4, s10, v60
	v_fmac_f32_e32 v4, s14, v61
	v_fmac_f32_e32 v4, s16, v62
	v_fmac_f32_e32 v4, s20, v63
	v_readlane_b32 s10, v2, 8
	v_readlane_b32 s14, v2, 9
	v_readlane_b32 s16, v2, 10
	v_readlane_b32 s20, v2, 11
	v_fmac_f32_e32 v4, s10, v64
	v_fmac_f32_e32 v4, s14, v65
	v_fmac_f32_e32 v4, s16, v66
	v_fmac_f32_e32 v4, s20, v67
	v_readlane_b32 s10, v2, 12
	v_readlane_b32 s14, v2, 13
	v_readlane_b32 s16, v2, 14
	v_readlane_b32 s20, v2, 15
	v_fmac_f32_e32 v4, s10, v68
	v_fmac_f32_e32 v4, s14, v69
	v_fmac_f32_e32 v4, s16, v70
	v_fmac_f32_e32 v4, s20, v71
	v_readlane_b32 s10, v2, 16
	v_readlane_b32 s14, v2, 17
	v_readlane_b32 s16, v2, 18
	v_readlane_b32 s20, v2, 19
	v_fmac_f32_e32 v4, s10, v72
	v_fmac_f32_e32 v4, s14, v73
	v_fmac_f32_e32 v4, s16, v74
	v_fmac_f32_e32 v4, s20, v75
	v_readlane_b32 s10, v2, 20
	v_readlane_b32 s14, v2, 21
	v_readlane_b32 s16, v2, 22
	v_readlane_b32 s20, v2, 23
	v_fmac_f32_e32 v4, s10, v76
	v_fmac_f32_e32 v4, s14, v77
	v_fmac_f32_e32 v4, s16, v78
	v_fmac_f32_e32 v4, s20, v79
	v_readlane_b32 s10, v2, 24
	v_readlane_b32 s14, v2, 25
	v_readlane_b32 s16, v2, 26
	v_readlane_b32 s20, v2, 27
	v_fmac_f32_e32 v4, s10, v80
	v_fmac_f32_e32 v4, s14, v81
	v_fmac_f32_e32 v4, s16, v82
	v_fmac_f32_e32 v4, s20, v83
	v_readlane_b32 s10, v2, 28
	v_readlane_b32 s14, v2, 29
	v_readlane_b32 s16, v2, 30
	v_readlane_b32 s20, v2, 31
	v_fmac_f32_e32 v4, s10, v84
	v_fmac_f32_e32 v4, s14, v85
	v_fmac_f32_e32 v4, s16, v86
	v_fmac_f32_e32 v4, s20, v87
	s_waitcnt lgkmcnt(0)
	v_readlane_b32 s10, v2, 32
	v_readlane_b32 s14, v2, 33
	v_readlane_b32 s16, v2, 34
	v_readlane_b32 s20, v2, 35
	v_fmac_f32_e32 v4, s10, v6
	v_fmac_f32_e32 v4, s14, v7
	v_fmac_f32_e32 v4, s16, v8
	v_fmac_f32_e32 v4, s20, v9
	v_readlane_b32 s10, v2, 36
	v_readlane_b32 s14, v2, 37
	v_readlane_b32 s16, v2, 38
	v_readlane_b32 s20, v2, 39
	v_fmac_f32_e32 v4, s10, v10
	v_fmac_f32_e32 v4, s14, v11
	v_fmac_f32_e32 v4, s16, v12
	v_fmac_f32_e32 v4, s20, v13
	v_readlane_b32 s10, v2, 40
	v_readlane_b32 s14, v2, 41
	v_readlane_b32 s16, v2, 42
	v_readlane_b32 s20, v2, 43
	v_fmac_f32_e32 v4, s10, v14
	v_fmac_f32_e32 v4, s14, v15
	v_fmac_f32_e32 v4, s16, v16
	v_fmac_f32_e32 v4, s20, v17
	v_readlane_b32 s10, v2, 44
	v_readlane_b32 s14, v2, 45
	v_readlane_b32 s16, v2, 46
	v_readlane_b32 s20, v2, 47
	v_fmac_f32_e32 v4, s10, v18
	v_fmac_f32_e32 v4, s14, v19
	v_fmac_f32_e32 v4, s16, v20
	v_fmac_f32_e32 v4, s20, v21
	v_readlane_b32 s10, v2, 48
	v_readlane_b32 s14, v2, 49
	v_readlane_b32 s16, v2, 50
	v_readlane_b32 s20, v2, 51
	v_fmac_f32_e32 v4, s10, v22
	v_fmac_f32_e32 v4, s14, v23
	v_fmac_f32_e32 v4, s16, v24
	v_fmac_f32_e32 v4, s20, v25
	v_readlane_b32 s10, v2, 52
	v_readlane_b32 s14, v2, 53
	v_readlane_b32 s16, v2, 54
	v_readlane_b32 s20, v2, 55
	v_fmac_f32_e32 v4, s10, v26
	v_fmac_f32_e32 v4, s14, v27
	v_fmac_f32_e32 v4, s16, v28
	v_fmac_f32_e32 v4, s20, v29
	v_readlane_b32 s10, v2, 56
	v_readlane_b32 s14, v2, 57
	v_readlane_b32 s16, v2, 58
	v_readlane_b32 s20, v2, 59
	v_fmac_f32_e32 v4, s10, v30
	v_fmac_f32_e32 v4, s14, v31
	v_fmac_f32_e32 v4, s16, v32
	v_fmac_f32_e32 v4, s20, v33
	v_readlane_b32 s10, v2, 60
	v_readlane_b32 s14, v2, 61
	v_readlane_b32 s16, v2, 62
	v_readlane_b32 s20, v2, 63
	v_fmac_f32_e32 v4, s10, v34
	v_fmac_f32_e32 v4, s14, v35
	v_fmac_f32_e32 v4, s16, v36
	v_fmac_f32_e32 v4, s20, v37
	v_mul_f32_e32 v2, 0.15915494, v4
	v_sin_f32_e32 v54, v2
	ds_read_b128 v[56:59], v103
	ds_read_b128 v[60:63], v103 offset:1024
	ds_read_b128 v[64:67], v103 offset:2048
	ds_read_b128 v[68:71], v103 offset:3072
	ds_read_b128 v[72:75], v103 offset:4096
	ds_read_b128 v[76:79], v103 offset:5120
	ds_read_b128 v[80:83], v103 offset:6144
	ds_read_b128 v[84:87], v103 offset:7168
	ds_read_b128 v[6:9], v103 offset:8192
	ds_read_b128 v[10:13], v103 offset:9216
	ds_read_b128 v[14:17], v103 offset:10240
	ds_read_b128 v[18:21], v103 offset:11264
	ds_read_b128 v[22:25], v103 offset:12288
	ds_read_b128 v[26:29], v103 offset:13312
	ds_read_b128 v[30:33], v103 offset:14336
	ds_read_b128 v[34:37], v103 offset:15360
	v_mov_b32_e32 v4, 0
	v_mov_b32_e32 v5, 0
	v_mov_b32_e32 v2, 0
	v_mov_b32_e32 v3, 0
	s_waitcnt lgkmcnt(8)
	v_readlane_b32 s10, v54, 0
	v_readlane_b32 s14, v54, 1
	v_readlane_b32 s16, v54, 2
	v_readlane_b32 s20, v54, 3
	v_pk_fma_f32 v[4:5], v[56:57], s[10:11], v[4:5] op_sel_hi:[1,0,1]
	v_pk_fma_f32 v[2:3], v[58:59], s[10:11], v[2:3] op_sel_hi:[1,0,1]
	v_pk_fma_f32 v[4:5], v[60:61], s[14:15], v[4:5] op_sel_hi:[1,0,1]
	v_pk_fma_f32 v[2:3], v[62:63], s[14:15], v[2:3] op_sel_hi:[1,0,1]
	v_pk_fma_f32 v[4:5], v[64:65], s[16:17], v[4:5] op_sel_hi:[1,0,1]
	v_pk_fma_f32 v[2:3], v[66:67], s[16:17], v[2:3] op_sel_hi:[1,0,1]
	v_pk_fma_f32 v[4:5], v[68:69], s[20:21], v[4:5] op_sel_hi:[1,0,1]
	v_pk_fma_f32 v[2:3], v[70:71], s[20:21], v[2:3] op_sel_hi:[1,0,1]
	v_readlane_b32 s10, v54, 4
	v_readlane_b32 s14, v54, 5
	v_readlane_b32 s16, v54, 6
	v_readlane_b32 s20, v54, 7
	v_pk_fma_f32 v[4:5], v[72:73], s[10:11], v[4:5] op_sel_hi:[1,0,1]
	v_pk_fma_f32 v[2:3], v[74:75], s[10:11], v[2:3] op_sel_hi:[1,0,1]
	v_pk_fma_f32 v[4:5], v[76:77], s[14:15], v[4:5] op_sel_hi:[1,0,1]
	v_pk_fma_f32 v[2:3], v[78:79], s[14:15], v[2:3] op_sel_hi:[1,0,1]
	v_pk_fma_f32 v[4:5], v[80:81], s[16:17], v[4:5] op_sel_hi:[1,0,1]
	v_pk_fma_f32 v[2:3], v[82:83], s[16:17], v[2:3] op_sel_hi:[1,0,1]
	v_pk_fma_f32 v[4:5], v[84:85], s[20:21], v[4:5] op_sel_hi:[1,0,1]
	v_pk_fma_f32 v[2:3], v[86:87], s[20:21], v[2:3] op_sel_hi:[1,0,1]
	ds_read_b128 v[56:59], v103 offset:16384
	ds_read_b128 v[60:63], v103 offset:17408
	ds_read_b128 v[64:67], v103 offset:18432
	ds_read_b128 v[68:71], v103 offset:19456
	ds_read_b128 v[72:75], v103 offset:20480
	ds_read_b128 v[76:79], v103 offset:21504
	ds_read_b128 v[80:83], v103 offset:22528
	ds_read_b128 v[84:87], v103 offset:23552
	s_waitcnt lgkmcnt(8)
; DI void filter_gen(const Inputs& in, int l, unsigned char* ws, LAS unsigned char* lds, int vcu, int G, int wave, int tid) {
;     ...
;         float o[4] = {0.f, 0.f, 0.f, 0.f};
; #pragma unroll 16
;         for (int k = 0; k < 64; ++k) { const float hk = __shfl(h2, k);
; #pragma unroll
;             for (int q = 0; q < 4; ++q) o[q] += hk * W3s[k * 256 + lane + 64 * q]; }
	v_readlane_b32 s10, v54, 8
	v_readlane_b32 s14, v54, 9
	v_readlane_b32 s16, v54, 10
	v_readlane_b32 s20, v54, 11
	v_pk_fma_f32 v[4:5], v[6:7], s[10:11], v[4:5] op_sel_hi:[1,0,1]
	v_pk_fma_f32 v[2:3], v[8:9], s[10:11], v[2:3] op_sel_hi:[1,0,1]
	v_pk_fma_f32 v[4:5], v[10:11], s[14:15], v[4:5] op_sel_hi:[1,0,1]
	v_pk_fma_f32 v[2:3], v[12:13], s[14:15], v[2:3] op_sel_hi:[1,0,1]
	v_pk_fma_f32 v[4:5], v[14:15], s[16:17], v[4:5] op_sel_hi:[1,0,1]
	v_pk_fma_f32 v[2:3], v[16:17], s[16:17], v[2:3] op_sel_hi:[1,0,1]
	v_pk_fma_f32 v[4:5], v[18:19], s[20:21], v[4:5] op_sel_hi:[1,0,1]
	v_pk_fma_f32 v[2:3], v[20:21], s[20:21], v[2:3] op_sel_hi:[1,0,1]
	v_readlane_b32 s10, v54, 12
	v_readlane_b32 s14, v54, 13
	v_readlane_b32 s16, v54, 14
	v_readlane_b32 s20, v54, 15
	v_pk_fma_f32 v[4:5], v[22:23], s[10:11], v[4:5] op_sel_hi:[1,0,1]
	v_pk_fma_f32 v[2:3], v[24:25], s[10:11], v[2:3] op_sel_hi:[1,0,1]
	v_pk_fma_f32 v[4:5], v[26:27], s[14:15], v[4:5] op_sel_hi:[1,0,1]
	v_pk_fma_f32 v[2:3], v[28:29], s[14:15], v[2:3] op_sel_hi:[1,0,1]
	v_pk_fma_f32 v[4:5], v[30:31], s[16:17], v[4:5] op_sel_hi:[1,0,1]
	v_pk_fma_f32 v[2:3], v[32:33], s[16:17], v[2:3] op_sel_hi:[1,0,1]
	v_pk_fma_f32 v[4:5], v[34:35], s[20:21], v[4:5] op_sel_hi:[1,0,1]
	v_pk_fma_f32 v[2:3], v[36:37], s[20:21], v[2:3] op_sel_hi:[1,0,1]
	ds_read_b128 v[6:9], v103 offset:24576
	ds_read_b128 v[10:13], v103 offset:25600
	ds_read_b128 v[14:17], v103 offset:26624
	ds_read_b128 v[18:21], v103 offset:27648
	ds_read_b128 v[22:25], v103 offset:28672
	ds_read_b128 v[26:29], v103 offset:29696
	ds_read_b128 v[30:33], v103 offset:30720
	ds_read_b128 v[34:37], v103 offset:31744
	s_waitcnt lgkmcnt(8)
	v_readlane_b32 s10, v54, 16
	v_readlane_b32 s14, v54, 17
	v_readlane_b32 s16, v54, 18
	v_readlane_b32 s20, v54, 19
	v_pk_fma_f32 v[4:5], v[56:57], s[10:11], v[4:5] op_sel_hi:[1,0,1]
	v_pk_fma_f32 v[2:3], v[58:59], s[10:11], v[2:3] op_sel_hi:[1,0,1]
	v_pk_fma_f32 v[4:5], v[60:61], s[14:15], v[4:5] op_sel_hi:[1,0,1]
	v_pk_fma_f32 v[2:3], v[62:63], s[14:15], v[2:3] op_sel_hi:[1,0,1]
	v_pk_fma_f32 v[4:5], v[64:65], s[16:17], v[4:5] op_sel_hi:[1,0,1]
	v_pk_fma_f32 v[2:3], v[66:67], s[16:17], v[2:3] op_sel_hi:[1,0,1]
	v_pk_fma_f32 v[4:5], v[68:69], s[20:21], v[4:5] op_sel_hi:[1,0,1]
	v_pk_fma_f32 v[2:3], v[70:71], s[20:21], v[2:3] op_sel_hi:[1,0,1]
	v_readlane_b32 s10, v54, 20
	v_readlane_b32 s14, v54, 21
	v_readlane_b32 s16, v54, 22
	v_readlane_b32 s20, v54, 23
	v_pk_fma_f32 v[4:5], v[72:73], s[10:11], v[4:5] op_sel_hi:[1,0,1]
	v_pk_fma_f32 v[2:3], v[74:75], s[10:11], v[2:3] op_sel_hi:[1,0,1]
	v_pk_fma_f32 v[4:5], v[76:77], s[14:15], v[4:5] op_sel_hi:[1,0,1]
	v_pk_fma_f32 v[2:3], v[78:79], s[14:15], v[2:3] op_sel_hi:[1,0,1]
	v_pk_fma_f32 v[4:5], v[80:81], s[16:17], v[4:5] op_sel_hi:[1,0,1]
	v_pk_fma_f32 v[2:3], v[82:83], s[16:17], v[2:3] op_sel_hi:[1,0,1]
	v_pk_fma_f32 v[4:5], v[84:85], s[20:21], v[4:5] op_sel_hi:[1,0,1]
	v_pk_fma_f32 v[2:3], v[86:87], s[20:21], v[2:3] op_sel_hi:[1,0,1]
	ds_read_b128 v[56:59], v103 offset:32768
	ds_read_b128 v[60:63], v103 offset:33792
	ds_read_b128 v[64:67], v103 offset:34816
	ds_read_b128 v[68:71], v103 offset:35840
	ds_read_b128 v[72:75], v103 offset:36864
	ds_read_b128 v[76:79], v103 offset:37888
	ds_read_b128 v[80:83], v103 offset:38912
	ds_read_b128 v[84:87], v103 offset:39936
	s_waitcnt lgkmcnt(8)
	v_readlane_b32 s10, v54, 24
	v_readlane_b32 s14, v54, 25
	v_readlane_b32 s16, v54, 26
	v_readlane_b32 s20, v54, 27
	v_pk_fma_f32 v[4:5], v[6:7], s[10:11], v[4:5] op_sel_hi:[1,0,1]
	v_pk_fma_f32 v[2:3], v[8:9], s[10:11], v[2:3] op_sel_hi:[1,0,1]
	v_pk_fma_f32 v[4:5], v[10:11], s[14:15], v[4:5] op_sel_hi:[1,0,1]
	v_pk_fma_f32 v[2:3], v[12:13], s[14:15], v[2:3] op_sel_hi:[1,0,1]
	v_pk_fma_f32 v[4:5], v[14:15], s[16:17], v[4:5] op_sel_hi:[1,0,1]
	v_pk_fma_f32 v[2:3], v[16:17], s[16:17], v[2:3] op_sel_hi:[1,0,1]
	v_pk_fma_f32 v[4:5], v[18:19], s[20:21], v[4:5] op_sel_hi:[1,0,1]
	v_pk_fma_f32 v[2:3], v[20:21], s[20:21], v[2:3] op_sel_hi:[1,0,1]
	v_readlane_b32 s10, v54, 28
	v_readlane_b32 s14, v54, 29
	v_readlane_b32 s16, v54, 30
	v_readlane_b32 s20, v54, 31
	v_pk_fma_f32 v[4:5], v[22:23], s[10:11], v[4:5] op_sel_hi:[1,0,1]
	v_pk_fma_f32 v[2:3], v[24:25], s[10:11], v[2:3] op_sel_hi:[1,0,1]
	v_pk_fma_f32 v[4:5], v[26:27], s[14:15], v[4:5] op_sel_hi:[1,0,1]
	v_pk_fma_f32 v[2:3], v[28:29], s[14:15], v[2:3] op_sel_hi:[1,0,1]
	v_pk_fma_f32 v[4:5], v[30:31], s[16:17], v[4:5] op_sel_hi:[1,0,1]
	v_pk_fma_f32 v[2:3], v[32:33], s[16:17], v[2:3] op_sel_hi:[1,0,1]
	v_pk_fma_f32 v[4:5], v[34:35], s[20:21], v[4:5] op_sel_hi:[1,0,1]
	v_pk_fma_f32 v[2:3], v[36:37], s[20:21], v[2:3] op_sel_hi:[1,0,1]
	ds_read_b128 v[6:9], v103 offset:40960
	ds_read_b128 v[10:13], v103 offset:41984
	ds_read_b128 v[14:17], v103 offset:43008
	ds_read_b128 v[18:21], v103 offset:44032
	ds_read_b128 v[22:25], v103 offset:45056
	ds_read_b128 v[26:29], v103 offset:46080
	ds_read_b128 v[30:33], v103 offset:47104
	ds_read_b128 v[34:37], v103 offset:48128
	s_waitcnt lgkmcnt(8)
; DI void filter_gen(const Inputs& in, int l, unsigned char* ws, LAS unsigned char* lds, int vcu, int G, int wave, int tid) {
;     ...
;         float o[4] = {0.f, 0.f, 0.f, 0.f};
; #pragma unroll 16
;         for (int k = 0; k < 64; ++k) { const float hk = __shfl(h2, k);
; #pragma unroll
;             for (int q = 0; q < 4; ++q) o[q] += hk * W3s[k * 256 + lane + 64 * q]; }
	v_readlane_b32 s10, v54, 32
	v_readlane_b32 s14, v54, 33
	v_readlane_b32 s16, v54, 34
	v_readlane_b32 s20, v54, 35
	v_pk_fma_f32 v[4:5], v[56:57], s[10:11], v[4:5] op_sel_hi:[1,0,1]
	v_pk_fma_f32 v[2:3], v[58:59], s[10:11], v[2:3] op_sel_hi:[1,0,1]
	v_pk_fma_f32 v[4:5], v[60:61], s[14:15], v[4:5] op_sel_hi:[1,0,1]
	v_pk_fma_f32 v[2:3], v[62:63], s[14:15], v[2:3] op_sel_hi:[1,0,1]
	v_pk_fma_f32 v[4:5], v[64:65], s[16:17], v[4:5] op_sel_hi:[1,0,1]
	v_pk_fma_f32 v[2:3], v[66:67], s[16:17], v[2:3] op_sel_hi:[1,0,1]
	v_pk_fma_f32 v[4:5], v[68:69], s[20:21], v[4:5] op_sel_hi:[1,0,1]
	v_pk_fma_f32 v[2:3], v[70:71], s[20:21], v[2:3] op_sel_hi:[1,0,1]
	v_readlane_b32 s10, v54, 36
	v_readlane_b32 s14, v54, 37
	v_readlane_b32 s16, v54, 38
	v_readlane_b32 s20, v54, 39
	v_pk_fma_f32 v[4:5], v[72:73], s[10:11], v[4:5] op_sel_hi:[1,0,1]
	v_pk_fma_f32 v[2:3], v[74:75], s[10:11], v[2:3] op_sel_hi:[1,0,1]
	v_pk_fma_f32 v[4:5], v[76:77], s[14:15], v[4:5] op_sel_hi:[1,0,1]
	v_pk_fma_f32 v[2:3], v[78:79], s[14:15], v[2:3] op_sel_hi:[1,0,1]
	v_pk_fma_f32 v[4:5], v[80:81], s[16:17], v[4:5] op_sel_hi:[1,0,1]
	v_pk_fma_f32 v[2:3], v[82:83], s[16:17], v[2:3] op_sel_hi:[1,0,1]
	v_pk_fma_f32 v[4:5], v[84:85], s[20:21], v[4:5] op_sel_hi:[1,0,1]
	v_pk_fma_f32 v[2:3], v[86:87], s[20:21], v[2:3] op_sel_hi:[1,0,1]
	ds_read_b128 v[56:59], v103 offset:49152
	ds_read_b128 v[60:63], v103 offset:50176
	ds_read_b128 v[64:67], v103 offset:51200
	ds_read_b128 v[68:71], v103 offset:52224
	ds_read_b128 v[72:75], v103 offset:53248
	ds_read_b128 v[76:79], v103 offset:54272
	ds_read_b128 v[80:83], v103 offset:55296
	ds_read_b128 v[84:87], v103 offset:56320
	s_waitcnt lgkmcnt(8)
	v_readlane_b32 s10, v54, 40
	v_readlane_b32 s14, v54, 41
	v_readlane_b32 s16, v54, 42
	v_readlane_b32 s20, v54, 43
	v_pk_fma_f32 v[4:5], v[6:7], s[10:11], v[4:5] op_sel_hi:[1,0,1]
	v_pk_fma_f32 v[2:3], v[8:9], s[10:11], v[2:3] op_sel_hi:[1,0,1]
	v_pk_fma_f32 v[4:5], v[10:11], s[14:15], v[4:5] op_sel_hi:[1,0,1]
	v_pk_fma_f32 v[2:3], v[12:13], s[14:15], v[2:3] op_sel_hi:[1,0,1]
	v_pk_fma_f32 v[4:5], v[14:15], s[16:17], v[4:5] op_sel_hi:[1,0,1]
	v_pk_fma_f32 v[2:3], v[16:17], s[16:17], v[2:3] op_sel_hi:[1,0,1]
	v_pk_fma_f32 v[4:5], v[18:19], s[20:21], v[4:5] op_sel_hi:[1,0,1]
	v_pk_fma_f32 v[2:3], v[20:21], s[20:21], v[2:3] op_sel_hi:[1,0,1]
	v_readlane_b32 s10, v54, 44
	v_readlane_b32 s14, v54, 45
	v_readlane_b32 s16, v54, 46
	v_readlane_b32 s20, v54, 47
	v_pk_fma_f32 v[4:5], v[22:23], s[10:11], v[4:5] op_sel_hi:[1,0,1]
	v_pk_fma_f32 v[2:3], v[24:25], s[10:11], v[2:3] op_sel_hi:[1,0,1]
	v_pk_fma_f32 v[4:5], v[26:27], s[14:15], v[4:5] op_sel_hi:[1,0,1]
	v_pk_fma_f32 v[2:3], v[28:29], s[14:15], v[2:3] op_sel_hi:[1,0,1]
	v_pk_fma_f32 v[4:5], v[30:31], s[16:17], v[4:5] op_sel_hi:[1,0,1]
	v_pk_fma_f32 v[2:3], v[32:33], s[16:17], v[2:3] op_sel_hi:[1,0,1]
	v_pk_fma_f32 v[4:5], v[34:35], s[20:21], v[4:5] op_sel_hi:[1,0,1]
	v_pk_fma_f32 v[2:3], v[36:37], s[20:21], v[2:3] op_sel_hi:[1,0,1]
	ds_read_b128 v[6:9], v103 offset:57344
	ds_read_b128 v[10:13], v103 offset:58368
	ds_read_b128 v[14:17], v103 offset:59392
	ds_read_b128 v[18:21], v103 offset:60416
	ds_read_b128 v[22:25], v103 offset:61440
	ds_read_b128 v[26:29], v103 offset:62464
	ds_read_b128 v[30:33], v103 offset:63488
	ds_read_b128 v[34:37], v103 offset:64512
	s_waitcnt lgkmcnt(8)
; DI void filter_gen(const Inputs& in, int l, unsigned char* ws, LAS unsigned char* lds, int vcu, int G, int wave, int tid) {
;     ...
;         float o[4] = {0.f, 0.f, 0.f, 0.f};
; #pragma unroll 16
;         for (int k = 0; k < 64; ++k) { const float hk = __shfl(h2, k);
; #pragma unroll
;             for (int q = 0; q < 4; ++q) o[q] += hk * W3s[k * 256 + lane + 64 * q]; }
; #pragma unroll
;         for (int q = 0; q < 4; ++q) {
;             const int cidx = 256 * chunk + lane + 64 * q, dir = cidx >> 9, c = cidx & 511;
;             const float delta = fabsf(-3.0701134573253942f + (float)c * ((-15.350567286626972f + 3.0701134573253942f) / 511.0f));
;             const float val = o[q] * __expf(-tl * delta);
;             bf16_t* row = FR + (size_t)c * FRS; bf16_t* rowo = FRO + (size_t)c * FRS;
;             if (dir == 0) { row[L - t] = f2bf(val); rowo[L - t - 1] = f2bf(val); }
;             else if (t >= 1) { row[L + t] = f2bf(val); rowo[L + t - 1] = f2bf(val); }
;         }
	v_readlane_b32 s10, v54, 48
	v_readlane_b32 s14, v54, 49
	v_readlane_b32 s16, v54, 50
	v_readlane_b32 s20, v54, 51
	v_pk_fma_f32 v[4:5], v[56:57], s[10:11], v[4:5] op_sel_hi:[1,0,1]
	v_pk_fma_f32 v[2:3], v[58:59], s[10:11], v[2:3] op_sel_hi:[1,0,1]
	v_pk_fma_f32 v[4:5], v[60:61], s[14:15], v[4:5] op_sel_hi:[1,0,1]
	v_pk_fma_f32 v[2:3], v[62:63], s[14:15], v[2:3] op_sel_hi:[1,0,1]
	v_pk_fma_f32 v[4:5], v[64:65], s[16:17], v[4:5] op_sel_hi:[1,0,1]
	v_pk_fma_f32 v[2:3], v[66:67], s[16:17], v[2:3] op_sel_hi:[1,0,1]
	v_pk_fma_f32 v[4:5], v[68:69], s[20:21], v[4:5] op_sel_hi:[1,0,1]
	v_pk_fma_f32 v[2:3], v[70:71], s[20:21], v[2:3] op_sel_hi:[1,0,1]
	v_readlane_b32 s10, v54, 52
	v_readlane_b32 s14, v54, 53
	v_readlane_b32 s16, v54, 54
	v_readlane_b32 s20, v54, 55
	v_pk_fma_f32 v[4:5], v[72:73], s[10:11], v[4:5] op_sel_hi:[1,0,1]
	v_pk_fma_f32 v[2:3], v[74:75], s[10:11], v[2:3] op_sel_hi:[1,0,1]
	v_pk_fma_f32 v[4:5], v[76:77], s[14:15], v[4:5] op_sel_hi:[1,0,1]
	v_pk_fma_f32 v[2:3], v[78:79], s[14:15], v[2:3] op_sel_hi:[1,0,1]
	v_pk_fma_f32 v[4:5], v[80:81], s[16:17], v[4:5] op_sel_hi:[1,0,1]
	v_pk_fma_f32 v[2:3], v[82:83], s[16:17], v[2:3] op_sel_hi:[1,0,1]
	v_pk_fma_f32 v[4:5], v[84:85], s[20:21], v[4:5] op_sel_hi:[1,0,1]
	v_pk_fma_f32 v[2:3], v[86:87], s[20:21], v[2:3] op_sel_hi:[1,0,1]
	s_waitcnt lgkmcnt(0)
	v_readlane_b32 s10, v54, 56
	v_readlane_b32 s14, v54, 57
	v_readlane_b32 s16, v54, 58
	v_readlane_b32 s20, v54, 59
	v_pk_fma_f32 v[4:5], v[6:7], s[10:11], v[4:5] op_sel_hi:[1,0,1]
	v_pk_fma_f32 v[2:3], v[8:9], s[10:11], v[2:3] op_sel_hi:[1,0,1]
	v_pk_fma_f32 v[4:5], v[10:11], s[14:15], v[4:5] op_sel_hi:[1,0,1]
	v_pk_fma_f32 v[2:3], v[12:13], s[14:15], v[2:3] op_sel_hi:[1,0,1]
	v_pk_fma_f32 v[4:5], v[14:15], s[16:17], v[4:5] op_sel_hi:[1,0,1]
	v_pk_fma_f32 v[2:3], v[16:17], s[16:17], v[2:3] op_sel_hi:[1,0,1]
	v_pk_fma_f32 v[4:5], v[18:19], s[20:21], v[4:5] op_sel_hi:[1,0,1]
	v_pk_fma_f32 v[2:3], v[20:21], s[20:21], v[2:3] op_sel_hi:[1,0,1]
	v_readlane_b32 s10, v54, 60
	v_readlane_b32 s14, v54, 61
	v_readlane_b32 s16, v54, 62
	v_readlane_b32 s20, v54, 63
	v_pk_fma_f32 v[4:5], v[22:23], s[10:11], v[4:5] op_sel_hi:[1,0,1]
	v_pk_fma_f32 v[2:3], v[24:25], s[10:11], v[2:3] op_sel_hi:[1,0,1]
	v_pk_fma_f32 v[4:5], v[26:27], s[14:15], v[4:5] op_sel_hi:[1,0,1]
	v_pk_fma_f32 v[2:3], v[28:29], s[14:15], v[2:3] op_sel_hi:[1,0,1]
	v_pk_fma_f32 v[4:5], v[30:31], s[16:17], v[4:5] op_sel_hi:[1,0,1]
	v_pk_fma_f32 v[2:3], v[32:33], s[16:17], v[2:3] op_sel_hi:[1,0,1]
	v_pk_fma_f32 v[4:5], v[34:35], s[20:21], v[4:5] op_sel_hi:[1,0,1]
	v_pk_fma_f32 v[2:3], v[36:37], s[20:21], v[2:3] op_sel_hi:[1,0,1]
	v_mul_f32_e64 v6, |v48|, v53
	v_mul_f32_e64 v7, |v49|, v53
	v_mul_f32_e64 v8, |v50|, v53
	v_mul_f32_e64 v9, |v51|, v53
	v_mul_f32_e32 v6, 0xbfb8aa3b, v6
	v_mul_f32_e32 v7, 0xbfb8aa3b, v7
	v_mul_f32_e32 v8, 0xbfb8aa3b, v8
	v_mul_f32_e32 v9, 0xbfb8aa3b, v9
	v_exp_f32_e32 v6, v6
	v_exp_f32_e32 v7, v7
	v_exp_f32_e32 v8, v8
	v_exp_f32_e32 v9, v9
	s_sub_i32 s10, s18, s59
	s_cmp_gt_u32 s59, 3
	s_cselect_b32 s11, 1, 0
	s_sub_i32 s14, s19, s10
	s_add_i32 s14, s14, -7
	s_add_i32 s15, s19, s10
	s_and_b64 s[20:21], s[12:13], exec
	s_cselect_b32 s14, s15, s14
	s_sub_i32 s14, s14, s11
	s_lshl_b32 s14, s14, 1
	s_and_b64 s[20:21], s[8:9], exec
	s_mov_b32 s15, 0xc10000
	s_cselect_b32 s15, s15, 0x400000
	s_mov_b32 s16, 0x1e510000
	s_cselect_b32 s16, s16, 0x1dd00000
	s_movk_i32 s24, 0x2040
	s_cselect_b32 s24, 0x1040, s24
	s_cmp_eq_u32 s11, 0
	s_cselect_b32 s15, s15, s16
	s_add_u32 s16, s34, s15
	s_addc_u32 s17, s35, 0
	s_add_u32 s16, s16, s14
	s_addc_u32 s17, s17, 0
	v_mul_f32_e32 v4, v6, v4
	v_mul_f32_e32 v5, v7, v5
	v_mul_f32_e32 v2, v8, v2
	v_mul_f32_e32 v3, v9, v3
	v_cvt_pk_bf16_f32 v4, v4, v4
	v_cvt_pk_bf16_f32 v5, v5, v5
	v_cvt_pk_bf16_f32 v2, v2, v2
	v_cvt_pk_bf16_f32 v3, v3, v3
	ds_write_b16 v100, v4
	ds_write_b16 v100, v5 offset:16
	ds_write_b16 v100, v2 offset:32
	ds_write_b16 v100, v3 offset:48
	s_waitcnt lgkmcnt(0)
	s_barrier
	ds_read_b128 v[96:99], v101
	v_xor_b32_e32 v100, 0x1000, v100
	v_mul_u32_u24_e32 v104, s24, v102
	v_mov_b32_e32 v105, 0
	v_lshlrev_b32_e32 v104, 1, v104
	v_xor_b32_e32 v101, 0x1000, v101
	s_and_b64 s[20:21], s[12:13], exec
	s_cselect_b32 s15, 1, 0
	s_cmp_eq_u32 s10, 0
	s_cselect_b32 s15, s15, 0
	v_lshl_add_u64 v[104:105], s[16:17], 0, v[104:105]
	s_cmp_lg_u32 s15, 0
	s_waitcnt lgkmcnt(0)
	s_cbranch_scc1 .Lfg_special_f3
	global_store_dwordx4 v[104:105], v[96:99], off
	s_branch .LBB0_1633
